# strip GEMM loops (QKV x2, pool-gemm, out-proj, FFN-down) also get their first K-iteration peeled with SrcC=0 first-touch MFMAs; accumulator zeroing removed in all 9 live GEMM loops
# baseline (speedup 1.0000x reference)
; #define GAS __attribute__((address_space(1)))
; #define PG8_ABASE(u) ((const GAS char*)g.A + (size_t)(u).pm * tstepA + (size_t)((u).pn / g.a_tpg) * (size_t)K * 2 + PG8_KOFF(u))
; #define PG8_BBASE(u) ((const GAS char*)g.Bt + (size_t)(u).pn * tstepB + PG8_KOFF(u))
; #define PG8_ABASE(u) ((const GAS char*)g.A + (size_t)(u).pm * tstepA + (size_t)((u).pn / g.a_tpg) * (size_t)K * 2 + PG8_KOFF(u))
; #define PG8_BBASE(u) ((const GAS char*)g.Bt + (size_t)(u).pn * tstepB + PG8_KOFF(u))
; #define PG8_SBASE(u) ((const GAS char*)g.A + (size_t)(u).srow * (size_t)lda * 2 + (size_t)((u).pn / g.a_tpg) * (size_t)K * 2 + PG8_KOFF(u))
; template <class Epi, class Sched>
; __device__ __forceinline__ void gemm_phase_strip(PG8_LAS unsigned char* lds, PG8_LAS unsigned char* slds, PG8_LAS unsigned char* pf, const Gemm g, const Sched& S, const Epi& E, int wv) {
;     ...
;         const bool has_next = S.next(ui + 1, nxt);
;         const GAS char* nA = has_next ? PG8_ABASE(nxt) : cA; const GAS char* nB = has_next ? PG8_BBASE(nxt) : cB; const GAS char* nS = has_next ? PG8_SBASE(nxt) : cS;
;         if constexpr (Sched::SPLIT) { if (has_next && nxt.kh > 0) nA += hstepA; }
;         int ntu = nt; if constexpr (Sched::SPLIT) { if (cur.kh >= 0) ntu = nt >> 1; }
;     ...
; #pragma unroll
;         for (int a = 0; a < 2; ++a)
; #pragma unroll
;             for (int b = 0; b < 2; ++b)
; #pragma unroll
;                 for (int m = 0; m < 4; ++m)
; #pragma unroll
;                     for (int n = 0; n < 2; ++n) acc[a][b][m][n] = (f32x4){0.f, 0.f, 0.f, 0.f};
;         accS[0] = (f32x4){0.f, 0.f, 0.f, 0.f}; accS[1] = (f32x4){0.f, 0.f, 0.f, 0.f};
;         cur = nxt; cA = nA; cB = nB; cS = nS; if constexpr (Sched::SPLIT) hsA = cur.kh > 0 ? -(long)hstepA : (long)hstepA; ++ui; par ^= 1;
.LBB0_242:
	s_ashr_i32 s85, s84, 31
	s_lshl_b64 s[14:15], s[84:85], 20
	v_readlane_b32 s1, v254, 63
	s_add_u32 s1, s1, s14
	v_readlane_b32 s5, v252, 0
	s_addc_u32 s5, s5, s15
	s_add_u32 s4, s1, s4
	s_addc_u32 s5, s5, 0
	s_and_b64 s[14:15], s[68:69], exec
	s_cselect_b32 s1, s5, s41
	s_cselect_b32 s11, s4, s40
	s_add_u32 s6, s2, s6
	s_addc_u32 s7, s3, s7
	s_cmp_lt_i32 s91, 0
	s_cselect_b64 s[14:15], -1, 0
	s_cmp_gt_i32 s91, -1
	s_cselect_b64 s[72:73], -1, 0
	s_and_b64 s[2:3], s[72:73], exec
	s_cselect_b32 s21, 16, 32
	s_and_b64 s[2:3], s[8:9], exec
	s_mov_b32 s2, 0xfff80000
	s_cselect_b32 s9, -1, 0
	s_cselect_b32 s8, s2, 0x80000
	s_add_u32 s22, s44, 0x100
	s_addc_u32 s23, s45, 0
	s_add_u32 s48, s40, 0x100
	s_addc_u32 s85, s41, 0
	s_add_u32 s2, s42, 0x80
	s_addc_u32 s3, s43, 0
	v_lshl_add_u64 v[0:1], s[2:3], 0, v[222:223]
	v_lshl_add_u64 v[226:227], v[0:1], 0, s[12:13]
	v_lshl_add_u64 v[0:1], s[2:3], 0, v[224:225]
	v_mov_b32_e32 v160, v161
	v_lshl_add_u64 v[228:229], v[0:1], 0, s[12:13]
	s_lshl_b32 s2, s21, 7
	v_mov_b32_e32 v162, v161
	v_mov_b32_e32 v163, v161
	v_mov_b64_e32 v[4:5], v[160:161]
	v_mov_b64_e32 v[0:1], v[160:161]
	s_mov_b32 s20, 0
	s_add_i32 s24, s2, 0xffffff00
	v_mov_b64_e32 v[6:7], v[162:163]
	v_mov_b64_e32 v[2:3], v[162:163]
	s_branch .Lpeel_s243

; #define GAS __attribute__((address_space(1)))
; #define PG8_STAGE(bufoff, gbase, voff) do { _Pragma("unroll") for (int _i = 0; _i < 2; ++_i) \
;         __builtin_amdgcn_global_load_lds((const GAS unsigned*)((const GAS char*)(gbase) + (voff)[_i]), (PG8_LAS unsigned*)(lds + (bufoff) + ldsw + _i * 8192), 16, 0, 0); } while (0)
; #define PG8_LDA(dst, b, h) do { _Pragma("unroll") for (int m = 0; m < 4; ++m) _Pragma("unroll") for (int k = 0; k < 2; ++k) dst[m][k] = *(const PG8_LAS bf16x8*)(lds + PG8_SA(b, h) + aoff + m * 2048 + k * 1024); } while (0)
; #define PG8_LDB(dst, b, h) do { _Pragma("unroll") for (int n = 0; n < 2; ++n) _Pragma("unroll") for (int k = 0; k < 2; ++k) dst[n][k] = *(const PG8_LAS bf16x8*)(lds + PG8_SB(b, h) + boff + n * 2048 + k * 1024); } while (0)
; #define PG8_MMA(ai, bj, At, Bt) do { __builtin_amdgcn_s_setprio(1); _Pragma("unroll") for (int m = 0; m < 4; ++m) _Pragma("unroll") for (int n = 0; n < 2; ++n) _Pragma("unroll") for (int k = 0; k < 2; ++k) \
;         acc[ai][bj][m][n] = __builtin_amdgcn_mfma_f32_16x16x32_bf16(Bt[n][k], At[m][k], acc[ai][bj][m][n], 0, 0, 0); __builtin_amdgcn_s_setprio(0); } while (0)
; #define PG8_WAIT_V(n) asm volatile("s_waitcnt vmcnt(" #n ")" ::: "memory")
; #define PG8_WAIT_L(n) asm volatile("s_waitcnt lgkmcnt(" #n ")" ::: "memory")
; #define PG8_BAR __builtin_amdgcn_s_barrier()
; #define PG8_SCHED __builtin_amdgcn_sched_barrier(0)
; #define PG8_WAIT_V(n) asm volatile("s_waitcnt vmcnt(" #n ")" ::: "memory")
; template <class Epi, class Sched>
; __device__ __forceinline__ void gemm_phase_strip(PG8_LAS unsigned char* lds, PG8_LAS unsigned char* slds, PG8_LAS unsigned char* pf, const Gemm g, const Sched& S, const Epi& E, int wv) {
;     ...
;         for (int t = 0; t < ntu; t += 2) {
;             const bool last = (t == ntu - 2);
;             const GAS char* a1 = cA + (size_t)(t + 1) * kstep;
;             const GAS char* a2 = last ? nA : cA + (size_t)(t + 2) * kstep; const GAS char* b2 = last ? nB : cB + (size_t)(t + 2) * kstep; const GAS char* s2 = last ? nS : cS + (size_t)(t + 2) * kstep;
;             const GAS char* a3 = a2 + kstep; const GAS char* b3 = b2 + kstep;
;             PG8_LDB(B0, 0, 0); PG8_LDB(B1, 0, 1); PG8_SCHED; PG8_LDA(At, 0, 0); PG8_STAGE(PG8_SA(1, 1), a1 + PG8_HS, voffA);
;             PG8_WAIT_V(8); PG8_WAIT_L(0); PG8_BAR; PG8_MMA(0, 0, At, B0); PG8_MMA(0, 1, At, B1); PG8_BAR; PG8_SCHED;
.Lpeel_s243:
	s_cmp_eq_u32 s24, s94
	s_cselect_b64 s[2:3], -1, 0
	s_add_u32 s25, s42, s94
	s_addc_u32 s28, s43, s95
	s_add_u32 s25, s25, 0x100
	s_addc_u32 s40, s28, 0
	s_and_b64 s[28:29], s[2:3], exec
	s_cselect_b32 s29, s7, s40
	s_cselect_b32 s28, s6, s25
	s_add_u32 s25, s48, s94
	s_addc_u32 s44, s85, s95
	s_add_i32 s66, 0, 0x10000
	v_add_u32_e32 v128, s66, v247
	s_add_i32 s67, 0, 0x14000
	ds_read_b128 v[156:159], v128
	ds_read_b128 v[152:155], v128 offset:1024
	ds_read_b128 v[174:177], v128 offset:2048
	ds_read_b128 v[170:173], v128 offset:3072
	v_add_u32_e32 v128, s67, v247
	ds_read_b128 v[166:169], v128
	ds_read_b128 v[162:165], v128 offset:1024
	ds_read_b128 v[182:185], v128 offset:2048
	ds_read_b128 v[178:181], v128 offset:3072
	s_and_b64 s[40:41], s[2:3], exec
	s_cselect_b32 s45, s1, s44
	s_cselect_b32 s44, s11, s25
	v_lshl_add_u64 v[136:137], v[228:229], 0, s[94:95]
	s_add_i32 m0, s53, 0xc000
	ds_read_b128 v[128:131], v250
	ds_read_b128 v[132:135], v250 offset:1024
	ds_read_b128 v[186:189], v250 offset:2048
	ds_read_b128 v[190:193], v250 offset:3072
	ds_read_b128 v[194:197], v250 offset:4096
	ds_read_b128 v[198:201], v250 offset:5120
	ds_read_b128 v[202:205], v250 offset:6144
	ds_read_b128 v[206:209], v250 offset:7168
	global_load_lds_dwordx4 v[136:137], off
	v_lshl_add_u64 v[136:137], v[226:227], 0, s[94:95]
	s_add_i32 m0, s53, 0xe000
	s_nop 0
	global_load_lds_dwordx4 v[136:137], off
	s_waitcnt vmcnt(8)
	s_waitcnt lgkmcnt(0)
	s_barrier
	s_waitcnt lgkmcnt(0)
	v_mfma_f32_16x16x32_bf16 v[136:139], v[156:159], v[128:131], 0
	v_mfma_f32_16x16x32_bf16 v[140:143], v[174:177], v[128:131], 0
	v_mfma_f32_16x16x32_bf16 v[116:119], v[156:159], v[186:189], 0
	v_mfma_f32_16x16x32_bf16 v[112:115], v[174:177], v[186:189], 0
	v_mfma_f32_16x16x32_bf16 v[100:103], v[156:159], v[194:197], 0
	v_mfma_f32_16x16x32_bf16 v[96:99], v[174:177], v[194:197], 0
	v_mfma_f32_16x16x32_bf16 v[84:87], v[156:159], v[202:205], 0
	v_mfma_f32_16x16x32_bf16 v[80:83], v[174:177], v[202:205], 0
	v_mfma_f32_16x16x32_bf16 v[136:139], v[152:155], v[132:135], v[136:139]
	v_mfma_f32_16x16x32_bf16 v[140:143], v[170:173], v[132:135], v[140:143]
	v_mfma_f32_16x16x32_bf16 v[116:119], v[152:155], v[190:193], v[116:119]
	v_mfma_f32_16x16x32_bf16 v[112:115], v[170:173], v[190:193], v[112:115]
	v_mfma_f32_16x16x32_bf16 v[100:103], v[152:155], v[198:201], v[100:103]
	v_mfma_f32_16x16x32_bf16 v[96:99], v[170:173], v[198:201], v[96:99]
	v_mfma_f32_16x16x32_bf16 v[84:87], v[152:155], v[206:209], v[84:87]
	v_mfma_f32_16x16x32_bf16 v[80:83], v[170:173], v[206:209], v[80:83]
	v_mfma_f32_16x16x32_bf16 v[124:127], v[166:169], v[128:131], 0
	v_mfma_f32_16x16x32_bf16 v[124:127], v[162:165], v[132:135], v[124:127]
	v_mfma_f32_16x16x32_bf16 v[120:123], v[182:185], v[128:131], 0
	v_mfma_f32_16x16x32_bf16 v[120:123], v[178:181], v[132:135], v[120:123]
	v_mfma_f32_16x16x32_bf16 v[108:111], v[166:169], v[186:189], 0
	v_mfma_f32_16x16x32_bf16 v[108:111], v[162:165], v[190:193], v[108:111]
	v_mfma_f32_16x16x32_bf16 v[104:107], v[182:185], v[186:189], 0
	v_mfma_f32_16x16x32_bf16 v[104:107], v[178:181], v[190:193], v[104:107]
	v_mfma_f32_16x16x32_bf16 v[92:95], v[166:169], v[194:197], 0
	v_mfma_f32_16x16x32_bf16 v[92:95], v[162:165], v[198:201], v[92:95]
	v_mfma_f32_16x16x32_bf16 v[88:91], v[182:185], v[194:197], 0
	v_mfma_f32_16x16x32_bf16 v[88:91], v[178:181], v[198:201], v[88:91]
	v_mfma_f32_16x16x32_bf16 v[76:79], v[166:169], v[202:205], 0
	v_mfma_f32_16x16x32_bf16 v[76:79], v[162:165], v[206:209], v[76:79]
	v_mfma_f32_16x16x32_bf16 v[72:75], v[182:185], v[202:205], 0
	v_mfma_f32_16x16x32_bf16 v[72:75], v[178:181], v[206:209], v[72:75]
	s_barrier
; #define PG8_STAGE(bufoff, gbase, voff) do { _Pragma("unroll") for (int _i = 0; _i < 2; ++_i) \
;         __builtin_amdgcn_global_load_lds((const GAS unsigned*)((const GAS char*)(gbase) + (voff)[_i]), (PG8_LAS unsigned*)(lds + (bufoff) + ldsw + _i * 8192), 16, 0, 0); } while (0)
; #define PG8_LDA(dst, b, h) do { _Pragma("unroll") for (int m = 0; m < 4; ++m) _Pragma("unroll") for (int k = 0; k < 2; ++k) dst[m][k] = *(const PG8_LAS bf16x8*)(lds + PG8_SA(b, h) + aoff + m * 2048 + k * 1024); } while (0)
; #define PG8_MMA(ai, bj, At, Bt) do { __builtin_amdgcn_s_setprio(1); _Pragma("unroll") for (int m = 0; m < 4; ++m) _Pragma("unroll") for (int n = 0; n < 2; ++n) _Pragma("unroll") for (int k = 0; k < 2; ++k) \
;         acc[ai][bj][m][n] = __builtin_amdgcn_mfma_f32_16x16x32_bf16(Bt[n][k], At[m][k], acc[ai][bj][m][n], 0, 0, 0); __builtin_amdgcn_s_setprio(0); } while (0)
; #define PG8_WAIT_V(n) asm volatile("s_waitcnt vmcnt(" #n ")" ::: "memory")
; #define PG8_WAIT_L(n) asm volatile("s_waitcnt lgkmcnt(" #n ")" ::: "memory")
; #define PG8_BAR __builtin_amdgcn_s_barrier()
; #define PG8_SCHED __builtin_amdgcn_sched_barrier(0)
; #define PG8_STAGE(bufoff, gbase, voff) do { _Pragma("unroll") for (int _i = 0; _i < 2; ++_i) \
;         __builtin_amdgcn_global_load_lds((const GAS unsigned*)((const GAS char*)(gbase) + (voff)[_i]), (PG8_LAS unsigned*)(lds + (bufoff) + ldsw + _i * 8192), 16, 0, 0); } while (0)
; #define PG8_LDA(dst, b, h) do { _Pragma("unroll") for (int m = 0; m < 4; ++m) _Pragma("unroll") for (int k = 0; k < 2; ++k) dst[m][k] = *(const PG8_LAS bf16x8*)(lds + PG8_SA(b, h) + aoff + m * 2048 + k * 1024); } while (0)
; #define PG8_LDS_S(dst, boffs) do { dst[0] = *(const PG8_LAS bf16x8*)(slds + (boffs) + soff0); dst[1] = *(const PG8_LAS bf16x8*)(slds + (boffs) + (soff0 ^ 64)); } while (0)
; #define PG8_BAR __builtin_amdgcn_s_barrier()
; template <class Epi, class Sched>
; __device__ __forceinline__ void gemm_phase_strip(PG8_LAS unsigned char* lds, PG8_LAS unsigned char* slds, PG8_LAS unsigned char* pf, const Gemm g, const Sched& S, const Epi& E, int wv) {
;     ...
;             PG8_LDA(At, 0, 1); PG8_LDS_S(As, sq); PG8_STAGE(PG8_SB(0, 0), b2, voffB); PG8_STAGE(PG8_SB(0, 1), b2 + hstepB, voffB); PG8_STAGE(PG8_SA(0, 0), a2, voffA);
;             PG8_WAIT_V(8); PG8_WAIT_L(0); PG8_BAR; PG8_MMA(1, 0, At, B0); PG8_MMA(1, 1, At, B1); PG8_MMA_S(); PG8_BAR; PG8_SCHED;
	s_add_i32 s25, s57, 0
	s_add_i32 s25, s25, 0x21000
	v_add_u32_e32 v160, s25, v248
	v_add_u32_e32 v251, s25, v249
	s_add_i32 s25, s66, s81
	v_lshl_add_u64 v[230:231], s[44:45], 0, v[216:217]
	s_mov_b32 m0, s25
	ds_read_b128 v[128:131], v250 offset:16384
	ds_read_b128 v[132:135], v250 offset:17408
	ds_read_b128 v[186:189], v250 offset:18432
	ds_read_b128 v[190:193], v250 offset:19456
	ds_read_b128 v[194:197], v250 offset:20480
	ds_read_b128 v[198:201], v250 offset:21504
	ds_read_b128 v[202:205], v250 offset:22528
	ds_read_b128 v[206:209], v250 offset:23552
	ds_read_b128 v[148:151], v160
	ds_read_b128 v[144:147], v251
	global_load_lds_dwordx4 v[230:231], off
	s_add_i32 m0, s25, 0x2000
	s_add_u32 s40, s44, 0x80000
	v_lshl_add_u64 v[232:233], s[44:45], 0, v[220:221]
	s_addc_u32 s41, s45, 0
	s_add_i32 s25, s67, s81
	global_load_lds_dwordx4 v[232:233], off
	v_lshl_add_u64 v[234:235], s[40:41], 0, v[216:217]
	s_mov_b32 m0, s25
	v_lshl_add_u64 v[236:237], s[28:29], 0, v[218:219]
	global_load_lds_dwordx4 v[234:235], off
	v_lshl_add_u64 v[234:235], s[40:41], 0, v[220:221]
	s_add_i32 m0, s25, 0x2000
	s_nop 0
	global_load_lds_dwordx4 v[234:235], off
	v_lshl_add_u64 v[234:235], s[28:29], 0, v[214:215]
	s_mov_b32 m0, s53
	s_nop 0
	global_load_lds_dwordx4 v[234:235], off
	s_mov_b32 m0, s97
	s_nop 0
	global_load_lds_dwordx4 v[236:237], off
	s_waitcnt vmcnt(8)
	s_waitcnt lgkmcnt(0)
	s_barrier
	s_waitcnt lgkmcnt(0)
	v_mfma_f32_16x16x32_bf16 v[68:71], v[156:159], v[128:131], 0
	v_mfma_f32_16x16x32_bf16 v[68:71], v[152:155], v[132:135], v[68:71]
	v_mfma_f32_16x16x32_bf16 v[64:67], v[174:177], v[128:131], 0
	v_mfma_f32_16x16x32_bf16 v[64:67], v[170:173], v[132:135], v[64:67]
	v_mfma_f32_16x16x32_bf16 v[52:55], v[156:159], v[186:189], 0
	v_mfma_f32_16x16x32_bf16 v[52:55], v[152:155], v[190:193], v[52:55]
	v_mfma_f32_16x16x32_bf16 v[48:51], v[174:177], v[186:189], 0
	v_mfma_f32_16x16x32_bf16 v[48:51], v[170:173], v[190:193], v[48:51]
	v_mfma_f32_16x16x32_bf16 v[36:39], v[156:159], v[194:197], 0
	v_mfma_f32_16x16x32_bf16 v[36:39], v[152:155], v[198:201], v[36:39]
	v_mfma_f32_16x16x32_bf16 v[32:35], v[174:177], v[194:197], 0
	v_mfma_f32_16x16x32_bf16 v[32:35], v[170:173], v[198:201], v[32:35]
	v_mfma_f32_16x16x32_bf16 v[20:23], v[156:159], v[202:205], 0
	v_mfma_f32_16x16x32_bf16 v[20:23], v[152:155], v[206:209], v[20:23]
	v_mfma_f32_16x16x32_bf16 v[16:19], v[174:177], v[202:205], 0
	v_mfma_f32_16x16x32_bf16 v[16:19], v[170:173], v[206:209], v[16:19]
	v_mfma_f32_16x16x32_bf16 v[60:63], v[166:169], v[128:131], 0
	v_mfma_f32_16x16x32_bf16 v[60:63], v[162:165], v[132:135], v[60:63]
	v_mfma_f32_16x16x32_bf16 v[56:59], v[182:185], v[128:131], 0
	v_mfma_f32_16x16x32_bf16 v[56:59], v[178:181], v[132:135], v[56:59]
	v_mfma_f32_16x16x32_bf16 v[44:47], v[166:169], v[186:189], 0
	v_mfma_f32_16x16x32_bf16 v[44:47], v[162:165], v[190:193], v[44:47]
	v_mfma_f32_16x16x32_bf16 v[40:43], v[182:185], v[186:189], 0
	v_mfma_f32_16x16x32_bf16 v[40:43], v[178:181], v[190:193], v[40:43]
	v_mfma_f32_16x16x32_bf16 v[28:31], v[166:169], v[194:197], 0
	v_mfma_f32_16x16x32_bf16 v[28:31], v[162:165], v[198:201], v[28:31]
	v_mfma_f32_16x16x32_bf16 v[24:27], v[182:185], v[194:197], 0
	v_mfma_f32_16x16x32_bf16 v[24:27], v[178:181], v[198:201], v[24:27]
	v_mfma_f32_16x16x32_bf16 v[12:15], v[166:169], v[202:205], 0
	v_mfma_f32_16x16x32_bf16 v[12:15], v[162:165], v[206:209], v[12:15]
	v_mfma_f32_16x16x32_bf16 v[8:11], v[182:185], v[202:205], 0
	v_mfma_f32_16x16x32_bf16 v[8:11], v[178:181], v[206:209], v[8:11]
	v_cndmask_b32_e64 v128, 0, 1, s[76:77]
	v_cmp_ne_u32_e64 s[40:41], 1, v128
	s_andn2_b64 vcc, exec, s[76:77]
	s_mov_b64 s[66:67], -1
	s_cbranch_vccnz .Lpk_s243_246
	v_mfma_f32_16x16x32_bf16 v[128:131], v[174:177], v[148:151], v[4:7]
	s_mov_b64 s[66:67], 0
	v_mfma_f32_16x16x32_bf16 v[132:135], v[182:185], v[148:151], v[0:3]
	v_mfma_f32_16x16x32_bf16 v[128:131], v[170:173], v[144:147], v[128:131]
	v_mfma_f32_16x16x32_bf16 v[132:135], v[178:181], v[144:147], v[132:135]

; #define GAS __attribute__((address_space(1)))
; #define PG8_ABASE(u) ((const GAS char*)g.A + (size_t)(u).pm * tstepA + (size_t)((u).pn / g.a_tpg) * (size_t)K * 2 + PG8_KOFF(u))
; #define PG8_BBASE(u) ((const GAS char*)g.Bt + (size_t)(u).pn * tstepB + PG8_KOFF(u))
; #define PG8_ABASE(u) ((const GAS char*)g.A + (size_t)(u).pm * tstepA + (size_t)((u).pn / g.a_tpg) * (size_t)K * 2 + PG8_KOFF(u))
; #define PG8_BBASE(u) ((const GAS char*)g.Bt + (size_t)(u).pn * tstepB + PG8_KOFF(u))
; #define PG8_SBASE(u) ((const GAS char*)g.A + (size_t)(u).srow * (size_t)lda * 2 + (size_t)((u).pn / g.a_tpg) * (size_t)K * 2 + PG8_KOFF(u))
; template <class Epi, class Sched>
; __device__ __forceinline__ void gemm_phase_strip(PG8_LAS unsigned char* lds, PG8_LAS unsigned char* slds, PG8_LAS unsigned char* pf, const Gemm g, const Sched& S, const Epi& E, int wv) {
;     ...
;         const bool has_next = S.next(ui + 1, nxt);
;         const GAS char* nA = has_next ? PG8_ABASE(nxt) : cA; const GAS char* nB = has_next ? PG8_BBASE(nxt) : cB; const GAS char* nS = has_next ? PG8_SBASE(nxt) : cS;
;         if constexpr (Sched::SPLIT) { if (has_next && nxt.kh > 0) nA += hstepA; }
;         int ntu = nt; if constexpr (Sched::SPLIT) { if (cur.kh >= 0) ntu = nt >> 1; }
;     ...
; #pragma unroll
;         for (int a = 0; a < 2; ++a)
; #pragma unroll
;             for (int b = 0; b < 2; ++b)
; #pragma unroll
;                 for (int m = 0; m < 4; ++m)
; #pragma unroll
;                     for (int n = 0; n < 2; ++n) acc[a][b][m][n] = (f32x4){0.f, 0.f, 0.f, 0.f};
;         accS[0] = (f32x4){0.f, 0.f, 0.f, 0.f}; accS[1] = (f32x4){0.f, 0.f, 0.f, 0.f};
;         cur = nxt; cA = nA; cB = nB; cS = nS; if constexpr (Sched::SPLIT) hsA = cur.kh > 0 ? -(long)hstepA : (long)hstepA; ++ui; par ^= 1;
.LBB0_537:
	s_ashr_i32 s53, s52, 31
	s_lshl_b64 s[2:3], s[52:53], 20
	s_add_u32 s62, s76, s2
	s_addc_u32 s63, s77, s3
	s_and_b64 s[2:3], s[40:41], exec
	s_cselect_b32 s21, s63, s69
	s_cselect_b32 s51, s62, s68
	s_add_u32 s53, s72, 0x100
	s_addc_u32 s55, s73, 0
	s_add_u32 s57, s68, 0x100
	s_addc_u32 s65, s69, 0
	s_add_u32 s2, s66, 0x80080
	s_addc_u32 s3, s67, 0
	v_mov_b32_e32 v8, 0
	v_lshl_add_u64 v[218:219], s[2:3], 0, v[214:215]
	v_lshl_add_u64 v[220:221], s[2:3], 0, v[216:217]
	s_mov_b32 s22, -2
	s_mov_b64 s[68:69], 0
	v_mov_b32_e32 v4, v8
	v_mov_b32_e32 v5, v8
	v_mov_b32_e32 v6, v8
	v_mov_b32_e32 v7, v8
	v_mov_b32_e32 v0, v8
	v_mov_b32_e32 v1, v8
	v_mov_b32_e32 v2, v8
	v_mov_b32_e32 v3, v8
	s_branch .Lpeel_s538

; #define GAS __attribute__((address_space(1)))
; #define PG8_STAGE(bufoff, gbase, voff) do { _Pragma("unroll") for (int _i = 0; _i < 2; ++_i) \
;         __builtin_amdgcn_global_load_lds((const GAS unsigned*)((const GAS char*)(gbase) + (voff)[_i]), (PG8_LAS unsigned*)(lds + (bufoff) + ldsw + _i * 8192), 16, 0, 0); } while (0)
; #define PG8_LDA(dst, b, h) do { _Pragma("unroll") for (int m = 0; m < 4; ++m) _Pragma("unroll") for (int k = 0; k < 2; ++k) dst[m][k] = *(const PG8_LAS bf16x8*)(lds + PG8_SA(b, h) + aoff + m * 2048 + k * 1024); } while (0)
; #define PG8_LDB(dst, b, h) do { _Pragma("unroll") for (int n = 0; n < 2; ++n) _Pragma("unroll") for (int k = 0; k < 2; ++k) dst[n][k] = *(const PG8_LAS bf16x8*)(lds + PG8_SB(b, h) + boff + n * 2048 + k * 1024); } while (0)
; #define PG8_MMA(ai, bj, At, Bt) do { __builtin_amdgcn_s_setprio(1); _Pragma("unroll") for (int m = 0; m < 4; ++m) _Pragma("unroll") for (int n = 0; n < 2; ++n) _Pragma("unroll") for (int k = 0; k < 2; ++k) \
;         acc[ai][bj][m][n] = __builtin_amdgcn_mfma_f32_16x16x32_bf16(Bt[n][k], At[m][k], acc[ai][bj][m][n], 0, 0, 0); __builtin_amdgcn_s_setprio(0); } while (0)
; #define PG8_WAIT_V(n) asm volatile("s_waitcnt vmcnt(" #n ")" ::: "memory")
; #define PG8_WAIT_L(n) asm volatile("s_waitcnt lgkmcnt(" #n ")" ::: "memory")
; #define PG8_BAR __builtin_amdgcn_s_barrier()
; #define PG8_SCHED __builtin_amdgcn_sched_barrier(0)
; #define PG8_WAIT_V(n) asm volatile("s_waitcnt vmcnt(" #n ")" ::: "memory")
; template <class Epi, class Sched>
; __device__ __forceinline__ void gemm_phase_strip(PG8_LAS unsigned char* lds, PG8_LAS unsigned char* slds, PG8_LAS unsigned char* pf, const Gemm g, const Sched& S, const Epi& E, int wv) {
;     ...
;         for (int t = 0; t < ntu; t += 2) {
;             const bool last = (t == ntu - 2);
;             const GAS char* a1 = cA + (size_t)(t + 1) * kstep;
;             const GAS char* a2 = last ? nA : cA + (size_t)(t + 2) * kstep; const GAS char* b2 = last ? nB : cB + (size_t)(t + 2) * kstep; const GAS char* s2 = last ? nS : cS + (size_t)(t + 2) * kstep;
;             const GAS char* a3 = a2 + kstep; const GAS char* b3 = b2 + kstep;
;             PG8_LDB(B0, 0, 0); PG8_LDB(B1, 0, 1); PG8_SCHED; PG8_LDA(At, 0, 0); PG8_STAGE(PG8_SA(1, 1), a1 + PG8_HS, voffA);
;             PG8_WAIT_V(8); PG8_WAIT_L(0); PG8_BAR; PG8_MMA(0, 0, At, B0); PG8_MMA(0, 1, At, B1); PG8_BAR; PG8_SCHED;
.Lpeel_s538:
	s_add_u32 s2, s66, s68
	s_addc_u32 s3, s67, s69
	s_add_u32 s23, s2, 0x100
	s_addc_u32 s28, s3, 0
	s_add_u32 s40, s57, s68
	s_addc_u32 s41, s65, s69
	s_add_i32 s74, 0, 0x10000
	s_add_i32 s75, 0, 0x14000
	v_add_u32_e32 v136, s74, v234
	ds_read_b128 v[148:151], v136
	ds_read_b128 v[144:147], v136 offset:1024
	ds_read_b128 v[166:169], v136 offset:2048
	ds_read_b128 v[162:165], v136 offset:3072
	v_add_u32_e32 v136, s75, v234
	ds_read_b128 v[156:159], v136
	ds_read_b128 v[152:155], v136 offset:1024
	ds_read_b128 v[174:177], v136 offset:2048
	ds_read_b128 v[170:173], v136 offset:3072
	s_cmpk_eq_i32 s68, 0xf00
	s_cselect_b64 s[2:3], -1, 0
	s_and_b64 s[24:25], s[2:3], exec
	s_cselect_b32 s29, s59, s28
	s_cselect_b32 s28, s58, s23
	s_cselect_b32 s73, s21, s41
	s_cselect_b32 s72, s51, s40
	v_lshl_add_u64 v[222:223], v[220:221], 0, s[68:69]
	s_add_i32 m0, s1, 0xc000
	ds_read_b128 v[136:139], v237
	ds_read_b128 v[140:143], v237 offset:1024
	ds_read_b128 v[178:181], v237 offset:2048
	ds_read_b128 v[182:185], v237 offset:3072
	ds_read_b128 v[186:189], v237 offset:4096
	ds_read_b128 v[190:193], v237 offset:5120
	ds_read_b128 v[194:197], v237 offset:6144
	ds_read_b128 v[198:201], v237 offset:7168
	global_load_lds_dwordx4 v[222:223], off
	v_lshl_add_u64 v[222:223], v[218:219], 0, s[68:69]
	s_add_i32 m0, s1, 0xe000
	s_nop 0
	global_load_lds_dwordx4 v[222:223], off
	s_waitcnt vmcnt(8)
	s_waitcnt lgkmcnt(0)
	s_barrier
	s_waitcnt lgkmcnt(0)
	v_mfma_f32_16x16x32_bf16 v[132:135], v[148:151], v[136:139], 0
	v_mfma_f32_16x16x32_bf16 v[132:135], v[144:147], v[140:143], v[132:135]
	v_mfma_f32_16x16x32_bf16 v[128:131], v[166:169], v[136:139], 0
	v_mfma_f32_16x16x32_bf16 v[128:131], v[162:165], v[140:143], v[128:131]
	v_mfma_f32_16x16x32_bf16 v[116:119], v[148:151], v[178:181], 0
	v_mfma_f32_16x16x32_bf16 v[116:119], v[144:147], v[182:185], v[116:119]
	v_mfma_f32_16x16x32_bf16 v[112:115], v[166:169], v[178:181], 0
	v_mfma_f32_16x16x32_bf16 v[112:115], v[162:165], v[182:185], v[112:115]
	v_mfma_f32_16x16x32_bf16 v[100:103], v[148:151], v[186:189], 0
	v_mfma_f32_16x16x32_bf16 v[100:103], v[144:147], v[190:193], v[100:103]
	v_mfma_f32_16x16x32_bf16 v[96:99], v[166:169], v[186:189], 0
	v_mfma_f32_16x16x32_bf16 v[96:99], v[162:165], v[190:193], v[96:99]
	v_mfma_f32_16x16x32_bf16 v[84:87], v[148:151], v[194:197], 0
	v_mfma_f32_16x16x32_bf16 v[84:87], v[144:147], v[198:201], v[84:87]
	v_mfma_f32_16x16x32_bf16 v[80:83], v[166:169], v[194:197], 0
	v_mfma_f32_16x16x32_bf16 v[80:83], v[162:165], v[198:201], v[80:83]
	v_mfma_f32_16x16x32_bf16 v[124:127], v[156:159], v[136:139], 0
	v_mfma_f32_16x16x32_bf16 v[124:127], v[152:155], v[140:143], v[124:127]
	v_mfma_f32_16x16x32_bf16 v[120:123], v[174:177], v[136:139], 0
	v_mfma_f32_16x16x32_bf16 v[120:123], v[170:173], v[140:143], v[120:123]
	v_mfma_f32_16x16x32_bf16 v[108:111], v[156:159], v[178:181], 0
	v_mfma_f32_16x16x32_bf16 v[108:111], v[152:155], v[182:185], v[108:111]
	v_mfma_f32_16x16x32_bf16 v[104:107], v[174:177], v[178:181], 0
	v_mfma_f32_16x16x32_bf16 v[104:107], v[170:173], v[182:185], v[104:107]
	v_mfma_f32_16x16x32_bf16 v[92:95], v[156:159], v[186:189], 0
	v_mfma_f32_16x16x32_bf16 v[92:95], v[152:155], v[190:193], v[92:95]
	v_mfma_f32_16x16x32_bf16 v[88:91], v[174:177], v[186:189], 0
	v_mfma_f32_16x16x32_bf16 v[88:91], v[170:173], v[190:193], v[88:91]
	v_mfma_f32_16x16x32_bf16 v[76:79], v[156:159], v[194:197], 0
	v_mfma_f32_16x16x32_bf16 v[76:79], v[152:155], v[198:201], v[76:79]
	v_mfma_f32_16x16x32_bf16 v[72:75], v[174:177], v[194:197], 0
	v_mfma_f32_16x16x32_bf16 v[72:75], v[170:173], v[198:201], v[72:75]
	s_barrier
; #define PG8_STAGE(bufoff, gbase, voff) do { _Pragma("unroll") for (int _i = 0; _i < 2; ++_i) \
;         __builtin_amdgcn_global_load_lds((const GAS unsigned*)((const GAS char*)(gbase) + (voff)[_i]), (PG8_LAS unsigned*)(lds + (bufoff) + ldsw + _i * 8192), 16, 0, 0); } while (0)
; #define PG8_LDA(dst, b, h) do { _Pragma("unroll") for (int m = 0; m < 4; ++m) _Pragma("unroll") for (int k = 0; k < 2; ++k) dst[m][k] = *(const PG8_LAS bf16x8*)(lds + PG8_SA(b, h) + aoff + m * 2048 + k * 1024); } while (0)
; #define PG8_MMA(ai, bj, At, Bt) do { __builtin_amdgcn_s_setprio(1); _Pragma("unroll") for (int m = 0; m < 4; ++m) _Pragma("unroll") for (int n = 0; n < 2; ++n) _Pragma("unroll") for (int k = 0; k < 2; ++k) \
;         acc[ai][bj][m][n] = __builtin_amdgcn_mfma_f32_16x16x32_bf16(Bt[n][k], At[m][k], acc[ai][bj][m][n], 0, 0, 0); __builtin_amdgcn_s_setprio(0); } while (0)
; #define PG8_WAIT_V(n) asm volatile("s_waitcnt vmcnt(" #n ")" ::: "memory")
; #define PG8_WAIT_L(n) asm volatile("s_waitcnt lgkmcnt(" #n ")" ::: "memory")
; #define PG8_BAR __builtin_amdgcn_s_barrier()
; #define PG8_SCHED __builtin_amdgcn_sched_barrier(0)
; #define PG8_STAGE(bufoff, gbase, voff) do { _Pragma("unroll") for (int _i = 0; _i < 2; ++_i) \
;         __builtin_amdgcn_global_load_lds((const GAS unsigned*)((const GAS char*)(gbase) + (voff)[_i]), (PG8_LAS unsigned*)(lds + (bufoff) + ldsw + _i * 8192), 16, 0, 0); } while (0)
; #define PG8_LDA(dst, b, h) do { _Pragma("unroll") for (int m = 0; m < 4; ++m) _Pragma("unroll") for (int k = 0; k < 2; ++k) dst[m][k] = *(const PG8_LAS bf16x8*)(lds + PG8_SA(b, h) + aoff + m * 2048 + k * 1024); } while (0)
; #define PG8_LDS_S(dst, boffs) do { dst[0] = *(const PG8_LAS bf16x8*)(slds + (boffs) + soff0); dst[1] = *(const PG8_LAS bf16x8*)(slds + (boffs) + (soff0 ^ 64)); } while (0)
; #define PG8_BAR __builtin_amdgcn_s_barrier()
; template <class Epi, class Sched>
; __device__ __forceinline__ void gemm_phase_strip(PG8_LAS unsigned char* lds, PG8_LAS unsigned char* slds, PG8_LAS unsigned char* pf, const Gemm g, const Sched& S, const Epi& E, int wv) {
;     ...
;             PG8_LDA(At, 0, 1); PG8_LDS_S(As, sq); PG8_STAGE(PG8_SB(0, 0), b2, voffB); PG8_STAGE(PG8_SB(0, 1), b2 + hstepB, voffB); PG8_STAGE(PG8_SA(0, 0), a2, voffA);
;             PG8_WAIT_V(8); PG8_WAIT_L(0); PG8_BAR; PG8_MMA(1, 0, At, B0); PG8_MMA(1, 1, At, B1); PG8_MMA_S(); PG8_BAR; PG8_SCHED;
	s_add_i32 s23, s34, 0
	s_add_i32 s23, s23, 0x21000
	v_add_u32_e32 v160, s23, v235
	v_add_u32_e32 v242, s23, v236
	s_add_i32 s23, s74, s79
	v_lshl_add_u64 v[222:223], s[72:73], 0, v[204:205]
	s_mov_b32 m0, s23
	ds_read_b128 v[136:139], v237 offset:16384
	ds_read_b128 v[140:143], v237 offset:17408
	ds_read_b128 v[186:189], v237 offset:18432
	ds_read_b128 v[190:193], v237 offset:19456
	ds_read_b128 v[194:197], v237 offset:20480
	ds_read_b128 v[198:201], v237 offset:21504
	ds_read_b128 v[244:247], v237 offset:22528
	ds_read_b128 v[248:251], v237 offset:23552
	ds_read_b128 v[182:185], v160
	ds_read_b128 v[178:181], v242
	global_load_lds_dwordx4 v[222:223], off
	s_add_i32 m0, s23, 0x2000
	s_add_u32 s24, s72, 0x80000
	v_lshl_add_u64 v[224:225], s[72:73], 0, v[208:209]
	s_addc_u32 s25, s73, 0
	s_add_i32 s23, s75, s79
	global_load_lds_dwordx4 v[224:225], off
	v_lshl_add_u64 v[226:227], s[24:25], 0, v[204:205]
	s_mov_b32 m0, s23
	v_lshl_add_u64 v[228:229], s[28:29], 0, v[206:207]
	global_load_lds_dwordx4 v[226:227], off
	v_lshl_add_u64 v[226:227], s[24:25], 0, v[208:209]
	s_add_i32 m0, s23, 0x2000
	s_nop 0
	global_load_lds_dwordx4 v[226:227], off
	v_lshl_add_u64 v[226:227], s[28:29], 0, v[202:203]
	s_mov_b32 m0, s1
	s_nop 0
	global_load_lds_dwordx4 v[226:227], off
	s_mov_b32 m0, s80
	s_nop 0
	global_load_lds_dwordx4 v[228:229], off
	s_waitcnt vmcnt(8)
	s_waitcnt lgkmcnt(0)
	s_barrier
	s_waitcnt lgkmcnt(0)
	v_mfma_f32_16x16x32_bf16 v[68:71], v[148:151], v[136:139], 0
	v_mfma_f32_16x16x32_bf16 v[68:71], v[144:147], v[140:143], v[68:71]
	v_mfma_f32_16x16x32_bf16 v[64:67], v[166:169], v[136:139], 0
	v_mfma_f32_16x16x32_bf16 v[64:67], v[162:165], v[140:143], v[64:67]
	v_mfma_f32_16x16x32_bf16 v[52:55], v[148:151], v[186:189], 0
	v_mfma_f32_16x16x32_bf16 v[52:55], v[144:147], v[190:193], v[52:55]
	v_mfma_f32_16x16x32_bf16 v[48:51], v[166:169], v[186:189], 0
	v_mfma_f32_16x16x32_bf16 v[48:51], v[162:165], v[190:193], v[48:51]
	v_mfma_f32_16x16x32_bf16 v[36:39], v[148:151], v[194:197], 0
	v_mfma_f32_16x16x32_bf16 v[36:39], v[144:147], v[198:201], v[36:39]
	v_mfma_f32_16x16x32_bf16 v[32:35], v[166:169], v[194:197], 0
	v_mfma_f32_16x16x32_bf16 v[32:35], v[162:165], v[198:201], v[32:35]
	v_mfma_f32_16x16x32_bf16 v[20:23], v[148:151], v[244:247], 0
	v_mfma_f32_16x16x32_bf16 v[20:23], v[144:147], v[248:251], v[20:23]
	v_mfma_f32_16x16x32_bf16 v[16:19], v[166:169], v[244:247], 0
	v_mfma_f32_16x16x32_bf16 v[16:19], v[162:165], v[248:251], v[16:19]
	v_mfma_f32_16x16x32_bf16 v[60:63], v[156:159], v[136:139], 0
	v_mfma_f32_16x16x32_bf16 v[60:63], v[152:155], v[140:143], v[60:63]
	v_mfma_f32_16x16x32_bf16 v[56:59], v[174:177], v[136:139], 0
	v_mfma_f32_16x16x32_bf16 v[56:59], v[170:173], v[140:143], v[56:59]
	v_mfma_f32_16x16x32_bf16 v[44:47], v[156:159], v[186:189], 0
	v_mfma_f32_16x16x32_bf16 v[44:47], v[152:155], v[190:193], v[44:47]
	v_mfma_f32_16x16x32_bf16 v[40:43], v[174:177], v[186:189], 0
	v_mfma_f32_16x16x32_bf16 v[40:43], v[170:173], v[190:193], v[40:43]
	v_mfma_f32_16x16x32_bf16 v[28:31], v[156:159], v[194:197], 0
	v_mfma_f32_16x16x32_bf16 v[28:31], v[152:155], v[198:201], v[28:31]
	v_mfma_f32_16x16x32_bf16 v[24:27], v[174:177], v[194:197], 0
	v_mfma_f32_16x16x32_bf16 v[24:27], v[170:173], v[198:201], v[24:27]
	v_mfma_f32_16x16x32_bf16 v[12:15], v[156:159], v[244:247], 0
	v_mfma_f32_16x16x32_bf16 v[12:15], v[152:155], v[248:251], v[12:15]
	v_mfma_f32_16x16x32_bf16 v[8:11], v[174:177], v[244:247], 0
	v_mfma_f32_16x16x32_bf16 v[8:11], v[170:173], v[248:251], v[8:11]
	v_cndmask_b32_e64 v136, 0, 1, s[42:43]
	v_cmp_ne_u32_e64 s[40:41], 1, v136
	s_andn2_b64 vcc, exec, s[42:43]
	s_mov_b64 s[74:75], -1
	s_cbranch_vccnz .Lpk_s538_541
	v_mfma_f32_16x16x32_bf16 v[136:139], v[166:169], v[182:185], v[4:7]
	s_mov_b64 s[74:75], 0
	v_mfma_f32_16x16x32_bf16 v[140:143], v[174:177], v[182:185], v[0:3]
	v_mfma_f32_16x16x32_bf16 v[136:139], v[162:165], v[178:181], v[136:139]
	v_mfma_f32_16x16x32_bf16 v[140:143], v[170:173], v[178:181], v[140:143]

; #define GAS __attribute__((address_space(1)))
; #define PG8_ABASE(u) ((const GAS char*)g.A + (size_t)(u).pm * tstepA + (size_t)((u).pn / g.a_tpg) * (size_t)K * 2 + PG8_KOFF(u))
; #define PG8_BBASE(u) ((const GAS char*)g.Bt + (size_t)(u).pn * tstepB + PG8_KOFF(u))
; #define PG8_ABASE(u) ((const GAS char*)g.A + (size_t)(u).pm * tstepA + (size_t)((u).pn / g.a_tpg) * (size_t)K * 2 + PG8_KOFF(u))
; #define PG8_BBASE(u) ((const GAS char*)g.Bt + (size_t)(u).pn * tstepB + PG8_KOFF(u))
; #define PG8_SBASE(u) ((const GAS char*)g.A + (size_t)(u).srow * (size_t)lda * 2 + (size_t)((u).pn / g.a_tpg) * (size_t)K * 2 + PG8_KOFF(u))
; template <class Epi, class Sched>
; __device__ __forceinline__ void gemm_phase_strip(PG8_LAS unsigned char* lds, PG8_LAS unsigned char* slds, PG8_LAS unsigned char* pf, const Gemm g, const Sched& S, const Epi& E, int wv) {
;     ...
;         const bool has_next = S.next(ui + 1, nxt);
;         const GAS char* nA = has_next ? PG8_ABASE(nxt) : cA; const GAS char* nB = has_next ? PG8_BBASE(nxt) : cB; const GAS char* nS = has_next ? PG8_SBASE(nxt) : cS;
;         if constexpr (Sched::SPLIT) { if (has_next && nxt.kh > 0) nA += hstepA; }
;         int ntu = nt; if constexpr (Sched::SPLIT) { if (cur.kh >= 0) ntu = nt >> 1; }
;     ...
; #pragma unroll
;         for (int a = 0; a < 2; ++a)
; #pragma unroll
;             for (int b = 0; b < 2; ++b)
; #pragma unroll
;                 for (int m = 0; m < 4; ++m)
; #pragma unroll
;                     for (int n = 0; n < 2; ++n) acc[a][b][m][n] = (f32x4){0.f, 0.f, 0.f, 0.f};
;         accS[0] = (f32x4){0.f, 0.f, 0.f, 0.f}; accS[1] = (f32x4){0.f, 0.f, 0.f, 0.f};
;         cur = nxt; cA = nA; cB = nB; cS = nS; if constexpr (Sched::SPLIT) hsA = cur.kh > 0 ? -(long)hstepA : (long)hstepA; ++ui; par ^= 1;
.LBB0_1107:
	s_ashr_i32 s43, s42, 31
	s_lshl_b64 s[20:21], s[42:43], 18
	s_add_u32 s54, s69, s20
	s_addc_u32 s55, s72, s21
	s_and_b64 s[20:21], s[38:39], exec
	s_cselect_b32 s1, s55, s15
	s_cselect_b32 s5, s54, s14
	s_add_u32 s11, s56, 0x100
	s_addc_u32 s20, s57, 0
	s_add_u32 s21, s14, 0x100
	s_addc_u32 s22, s15, 0
	s_add_u32 s14, s12, 0x80080
	v_mov_b32_e32 v160, v161
	s_addc_u32 s15, s13, 0
	v_mov_b32_e32 v162, v161
	v_mov_b32_e32 v163, v161
	v_mov_b64_e32 v[4:5], v[160:161]
	s_waitcnt lgkmcnt(0)
	v_mov_b64_e32 v[0:1], v[160:161]
	v_lshl_add_u64 v[218:219], s[14:15], 0, v[214:215]
	v_lshl_add_u64 v[220:221], s[14:15], 0, v[216:217]
	s_mov_b32 s23, -2
	s_mov_b64 s[14:15], 0
	v_mov_b64_e32 v[6:7], v[162:163]
	v_mov_b64_e32 v[2:3], v[162:163]
	s_branch .Lpeel_s1108

; #define GAS __attribute__((address_space(1)))
; #define PG8_STAGE(bufoff, gbase, voff) do { _Pragma("unroll") for (int _i = 0; _i < 2; ++_i) \
;         __builtin_amdgcn_global_load_lds((const GAS unsigned*)((const GAS char*)(gbase) + (voff)[_i]), (PG8_LAS unsigned*)(lds + (bufoff) + ldsw + _i * 8192), 16, 0, 0); } while (0)
; #define PG8_LDA(dst, b, h) do { _Pragma("unroll") for (int m = 0; m < 4; ++m) _Pragma("unroll") for (int k = 0; k < 2; ++k) dst[m][k] = *(const PG8_LAS bf16x8*)(lds + PG8_SA(b, h) + aoff + m * 2048 + k * 1024); } while (0)
; #define PG8_LDB(dst, b, h) do { _Pragma("unroll") for (int n = 0; n < 2; ++n) _Pragma("unroll") for (int k = 0; k < 2; ++k) dst[n][k] = *(const PG8_LAS bf16x8*)(lds + PG8_SB(b, h) + boff + n * 2048 + k * 1024); } while (0)
; #define PG8_MMA(ai, bj, At, Bt) do { __builtin_amdgcn_s_setprio(1); _Pragma("unroll") for (int m = 0; m < 4; ++m) _Pragma("unroll") for (int n = 0; n < 2; ++n) _Pragma("unroll") for (int k = 0; k < 2; ++k) \
;         acc[ai][bj][m][n] = __builtin_amdgcn_mfma_f32_16x16x32_bf16(Bt[n][k], At[m][k], acc[ai][bj][m][n], 0, 0, 0); __builtin_amdgcn_s_setprio(0); } while (0)
; #define PG8_WAIT_V(n) asm volatile("s_waitcnt vmcnt(" #n ")" ::: "memory")
; #define PG8_WAIT_L(n) asm volatile("s_waitcnt lgkmcnt(" #n ")" ::: "memory")
; #define PG8_BAR __builtin_amdgcn_s_barrier()
; #define PG8_SCHED __builtin_amdgcn_sched_barrier(0)
; #define PG8_WAIT_V(n) asm volatile("s_waitcnt vmcnt(" #n ")" ::: "memory")
; template <class Epi, class Sched>
; __device__ __forceinline__ void gemm_phase_strip(PG8_LAS unsigned char* lds, PG8_LAS unsigned char* slds, PG8_LAS unsigned char* pf, const Gemm g, const Sched& S, const Epi& E, int wv) {
;     ...
;         for (int t = 0; t < ntu; t += 2) {
;             const bool last = (t == ntu - 2);
;             const GAS char* a1 = cA + (size_t)(t + 1) * kstep;
;             const GAS char* a2 = last ? nA : cA + (size_t)(t + 2) * kstep; const GAS char* b2 = last ? nB : cB + (size_t)(t + 2) * kstep; const GAS char* s2 = last ? nS : cS + (size_t)(t + 2) * kstep;
;             const GAS char* a3 = a2 + kstep; const GAS char* b3 = b2 + kstep;
;             PG8_LDB(B0, 0, 0); PG8_LDB(B1, 0, 1); PG8_SCHED; PG8_LDA(At, 0, 0); PG8_STAGE(PG8_SA(1, 1), a1 + PG8_HS, voffA);
;             PG8_WAIT_V(8); PG8_WAIT_L(0); PG8_BAR; PG8_MMA(0, 0, At, B0); PG8_MMA(0, 1, At, B1); PG8_BAR; PG8_SCHED;
.Lpeel_s1108:
	s_add_u32 s24, s12, s14
	s_addc_u32 s25, s13, s15
	s_add_u32 s28, s24, 0x100
	s_addc_u32 s29, s25, 0
	s_add_u32 s38, s21, s14
	s_addc_u32 s39, s22, s15
	s_add_i32 s41, 0, 0x10000
	s_add_i32 s43, 0, 0x14000
	v_add_u32_e32 v132, s41, v233
	ds_read_b128 v[148:151], v132
	ds_read_b128 v[144:147], v132 offset:1024
	ds_read_b128 v[166:169], v132 offset:2048
	ds_read_b128 v[162:165], v132 offset:3072
	v_add_u32_e32 v132, s43, v233
	ds_read_b128 v[156:159], v132
	ds_read_b128 v[152:155], v132 offset:1024
	ds_read_b128 v[174:177], v132 offset:2048
	ds_read_b128 v[170:173], v132 offset:3072
	s_cmpk_eq_i32 s14, 0x300
	s_cselect_b64 s[58:59], -1, 0
	s_and_b64 s[24:25], s[58:59], exec
	s_cselect_b32 s29, s51, s29
	s_cselect_b32 s28, s50, s28
	s_cselect_b32 s57, s1, s39
	s_cselect_b32 s56, s5, s38
	v_lshl_add_u64 v[222:223], v[220:221], 0, s[14:15]
	s_add_i32 m0, s19, 0xc000
	ds_read_b128 v[132:135], v236
	ds_read_b128 v[140:143], v236 offset:1024
	ds_read_b128 v[178:181], v236 offset:2048
	ds_read_b128 v[182:185], v236 offset:3072
	ds_read_b128 v[186:189], v236 offset:4096
	ds_read_b128 v[190:193], v236 offset:5120
	ds_read_b128 v[194:197], v236 offset:6144
	ds_read_b128 v[198:201], v236 offset:7168
	global_load_lds_dwordx4 v[222:223], off
	v_lshl_add_u64 v[222:223], v[218:219], 0, s[14:15]
	s_add_i32 m0, s19, 0xe000
	s_nop 0
	global_load_lds_dwordx4 v[222:223], off
	s_waitcnt vmcnt(8)
	s_waitcnt lgkmcnt(0)
	s_barrier
	s_waitcnt lgkmcnt(0)
	v_mfma_f32_16x16x32_bf16 v[136:139], v[148:151], v[132:135], 0
	v_mfma_f32_16x16x32_bf16 v[136:139], v[144:147], v[140:143], v[136:139]
	v_mfma_f32_16x16x32_bf16 v[128:131], v[166:169], v[132:135], 0
	v_mfma_f32_16x16x32_bf16 v[128:131], v[162:165], v[140:143], v[128:131]
	v_mfma_f32_16x16x32_bf16 v[124:127], v[148:151], v[178:181], 0
	v_mfma_f32_16x16x32_bf16 v[124:127], v[144:147], v[182:185], v[124:127]
	v_mfma_f32_16x16x32_bf16 v[120:123], v[166:169], v[178:181], 0
	v_mfma_f32_16x16x32_bf16 v[120:123], v[162:165], v[182:185], v[120:123]
	v_mfma_f32_16x16x32_bf16 v[116:119], v[148:151], v[186:189], 0
	v_mfma_f32_16x16x32_bf16 v[116:119], v[144:147], v[190:193], v[116:119]
	v_mfma_f32_16x16x32_bf16 v[112:115], v[166:169], v[186:189], 0
	v_mfma_f32_16x16x32_bf16 v[112:115], v[162:165], v[190:193], v[112:115]
	v_mfma_f32_16x16x32_bf16 v[108:111], v[148:151], v[194:197], 0
	v_mfma_f32_16x16x32_bf16 v[108:111], v[144:147], v[198:201], v[108:111]
	v_mfma_f32_16x16x32_bf16 v[104:107], v[166:169], v[194:197], 0
	v_mfma_f32_16x16x32_bf16 v[104:107], v[162:165], v[198:201], v[104:107]
	v_mfma_f32_16x16x32_bf16 v[68:71], v[156:159], v[132:135], 0
	v_mfma_f32_16x16x32_bf16 v[68:71], v[152:155], v[140:143], v[68:71]
	v_mfma_f32_16x16x32_bf16 v[64:67], v[174:177], v[132:135], 0
	v_mfma_f32_16x16x32_bf16 v[64:67], v[170:173], v[140:143], v[64:67]
	v_mfma_f32_16x16x32_bf16 v[60:63], v[156:159], v[178:181], 0
	v_mfma_f32_16x16x32_bf16 v[60:63], v[152:155], v[182:185], v[60:63]
	v_mfma_f32_16x16x32_bf16 v[56:59], v[174:177], v[178:181], 0
	v_mfma_f32_16x16x32_bf16 v[56:59], v[170:173], v[182:185], v[56:59]
	v_mfma_f32_16x16x32_bf16 v[52:55], v[156:159], v[186:189], 0
	v_mfma_f32_16x16x32_bf16 v[52:55], v[152:155], v[190:193], v[52:55]
	v_mfma_f32_16x16x32_bf16 v[48:51], v[174:177], v[186:189], 0
	v_mfma_f32_16x16x32_bf16 v[48:51], v[170:173], v[190:193], v[48:51]
	v_mfma_f32_16x16x32_bf16 v[44:47], v[156:159], v[194:197], 0
	v_mfma_f32_16x16x32_bf16 v[44:47], v[152:155], v[198:201], v[44:47]
	v_mfma_f32_16x16x32_bf16 v[40:43], v[174:177], v[194:197], 0
	v_mfma_f32_16x16x32_bf16 v[40:43], v[170:173], v[198:201], v[40:43]
	s_barrier
; #define PG8_STAGE(bufoff, gbase, voff) do { _Pragma("unroll") for (int _i = 0; _i < 2; ++_i) \
;         __builtin_amdgcn_global_load_lds((const GAS unsigned*)((const GAS char*)(gbase) + (voff)[_i]), (PG8_LAS unsigned*)(lds + (bufoff) + ldsw + _i * 8192), 16, 0, 0); } while (0)
; #define PG8_LDA(dst, b, h) do { _Pragma("unroll") for (int m = 0; m < 4; ++m) _Pragma("unroll") for (int k = 0; k < 2; ++k) dst[m][k] = *(const PG8_LAS bf16x8*)(lds + PG8_SA(b, h) + aoff + m * 2048 + k * 1024); } while (0)
; #define PG8_MMA(ai, bj, At, Bt) do { __builtin_amdgcn_s_setprio(1); _Pragma("unroll") for (int m = 0; m < 4; ++m) _Pragma("unroll") for (int n = 0; n < 2; ++n) _Pragma("unroll") for (int k = 0; k < 2; ++k) \
;         acc[ai][bj][m][n] = __builtin_amdgcn_mfma_f32_16x16x32_bf16(Bt[n][k], At[m][k], acc[ai][bj][m][n], 0, 0, 0); __builtin_amdgcn_s_setprio(0); } while (0)
; #define PG8_WAIT_V(n) asm volatile("s_waitcnt vmcnt(" #n ")" ::: "memory")
; #define PG8_WAIT_L(n) asm volatile("s_waitcnt lgkmcnt(" #n ")" ::: "memory")
; #define PG8_BAR __builtin_amdgcn_s_barrier()
; #define PG8_SCHED __builtin_amdgcn_sched_barrier(0)
; #define PG8_STAGE(bufoff, gbase, voff) do { _Pragma("unroll") for (int _i = 0; _i < 2; ++_i) \
;         __builtin_amdgcn_global_load_lds((const GAS unsigned*)((const GAS char*)(gbase) + (voff)[_i]), (PG8_LAS unsigned*)(lds + (bufoff) + ldsw + _i * 8192), 16, 0, 0); } while (0)
; #define PG8_LDA(dst, b, h) do { _Pragma("unroll") for (int m = 0; m < 4; ++m) _Pragma("unroll") for (int k = 0; k < 2; ++k) dst[m][k] = *(const PG8_LAS bf16x8*)(lds + PG8_SA(b, h) + aoff + m * 2048 + k * 1024); } while (0)
; #define PG8_LDS_S(dst, boffs) do { dst[0] = *(const PG8_LAS bf16x8*)(slds + (boffs) + soff0); dst[1] = *(const PG8_LAS bf16x8*)(slds + (boffs) + (soff0 ^ 64)); } while (0)
; #define PG8_BAR __builtin_amdgcn_s_barrier()
; template <class Epi, class Sched>
; __device__ __forceinline__ void gemm_phase_strip(PG8_LAS unsigned char* lds, PG8_LAS unsigned char* slds, PG8_LAS unsigned char* pf, const Gemm g, const Sched& S, const Epi& E, int wv) {
;     ...
;             PG8_LDA(At, 0, 1); PG8_LDS_S(As, sq); PG8_STAGE(PG8_SB(0, 0), b2, voffB); PG8_STAGE(PG8_SB(0, 1), b2 + hstepB, voffB); PG8_STAGE(PG8_SA(0, 0), a2, voffA);
;             PG8_WAIT_V(8); PG8_WAIT_L(0); PG8_BAR; PG8_MMA(1, 0, At, B0); PG8_MMA(1, 1, At, B1); PG8_MMA_S(); PG8_BAR; PG8_SCHED;
	s_add_i32 s24, s97, 0
	s_add_i32 s24, s24, 0x21000
	v_add_u32_e32 v160, s24, v234
	v_add_u32_e32 v237, s24, v235
	s_add_i32 s24, s41, s81
	v_lshl_add_u64 v[222:223], s[56:57], 0, v[204:205]
	s_mov_b32 m0, s24
	ds_read_b128 v[132:135], v236 offset:16384
	ds_read_b128 v[140:143], v236 offset:17408
	ds_read_b128 v[186:189], v236 offset:18432
	ds_read_b128 v[190:193], v236 offset:19456
	ds_read_b128 v[194:197], v236 offset:20480
	ds_read_b128 v[198:201], v236 offset:21504
	ds_read_b128 v[242:245], v236 offset:22528
	ds_read_b128 v[246:249], v236 offset:23552
	ds_read_b128 v[182:185], v160
	ds_read_b128 v[178:181], v237
	global_load_lds_dwordx4 v[222:223], off
	s_add_i32 m0, s24, 0x2000
	s_add_u32 s24, s56, 0x20000
	v_lshl_add_u64 v[224:225], s[56:57], 0, v[208:209]
	s_addc_u32 s25, s57, 0
	s_add_i32 s38, s43, s81
	global_load_lds_dwordx4 v[224:225], off
	v_lshl_add_u64 v[226:227], s[24:25], 0, v[204:205]
	s_mov_b32 m0, s38
	v_lshl_add_u64 v[228:229], s[28:29], 0, v[206:207]
	global_load_lds_dwordx4 v[226:227], off
	v_lshl_add_u64 v[226:227], s[24:25], 0, v[208:209]
	s_add_i32 m0, s38, 0x2000
	s_nop 0
	global_load_lds_dwordx4 v[226:227], off
	v_lshl_add_u64 v[226:227], s[28:29], 0, v[202:203]
	s_mov_b32 m0, s19
	s_nop 0
	global_load_lds_dwordx4 v[226:227], off
	s_mov_b32 m0, s27
	s_nop 0
	global_load_lds_dwordx4 v[228:229], off
	s_waitcnt vmcnt(8)
	s_waitcnt lgkmcnt(0)
	s_barrier
	s_waitcnt lgkmcnt(0)
	v_mfma_f32_16x16x32_bf16 v[100:103], v[148:151], v[132:135], 0
	v_mfma_f32_16x16x32_bf16 v[100:103], v[144:147], v[140:143], v[100:103]
	v_mfma_f32_16x16x32_bf16 v[96:99], v[166:169], v[132:135], 0
	v_mfma_f32_16x16x32_bf16 v[96:99], v[162:165], v[140:143], v[96:99]
	v_mfma_f32_16x16x32_bf16 v[92:95], v[148:151], v[186:189], 0
	v_mfma_f32_16x16x32_bf16 v[92:95], v[144:147], v[190:193], v[92:95]
	v_mfma_f32_16x16x32_bf16 v[88:91], v[166:169], v[186:189], 0
	v_mfma_f32_16x16x32_bf16 v[88:91], v[162:165], v[190:193], v[88:91]
	v_mfma_f32_16x16x32_bf16 v[84:87], v[148:151], v[194:197], 0
	v_mfma_f32_16x16x32_bf16 v[84:87], v[144:147], v[198:201], v[84:87]
	v_mfma_f32_16x16x32_bf16 v[80:83], v[166:169], v[194:197], 0
	v_mfma_f32_16x16x32_bf16 v[80:83], v[162:165], v[198:201], v[80:83]
	v_mfma_f32_16x16x32_bf16 v[76:79], v[148:151], v[242:245], 0
	v_mfma_f32_16x16x32_bf16 v[76:79], v[144:147], v[246:249], v[76:79]
	v_mfma_f32_16x16x32_bf16 v[72:75], v[166:169], v[242:245], 0
	v_mfma_f32_16x16x32_bf16 v[72:75], v[162:165], v[246:249], v[72:75]
	v_mfma_f32_16x16x32_bf16 v[36:39], v[156:159], v[132:135], 0
	v_mfma_f32_16x16x32_bf16 v[36:39], v[152:155], v[140:143], v[36:39]
	v_mfma_f32_16x16x32_bf16 v[32:35], v[174:177], v[132:135], 0
	v_mfma_f32_16x16x32_bf16 v[32:35], v[170:173], v[140:143], v[32:35]
	v_mfma_f32_16x16x32_bf16 v[28:31], v[156:159], v[186:189], 0
	v_mfma_f32_16x16x32_bf16 v[28:31], v[152:155], v[190:193], v[28:31]
	v_mfma_f32_16x16x32_bf16 v[24:27], v[174:177], v[186:189], 0
	v_mfma_f32_16x16x32_bf16 v[24:27], v[170:173], v[190:193], v[24:27]
	v_mfma_f32_16x16x32_bf16 v[20:23], v[156:159], v[194:197], 0
	v_mfma_f32_16x16x32_bf16 v[20:23], v[152:155], v[198:201], v[20:23]
	v_mfma_f32_16x16x32_bf16 v[16:19], v[174:177], v[194:197], 0
	v_mfma_f32_16x16x32_bf16 v[16:19], v[170:173], v[198:201], v[16:19]
	v_mfma_f32_16x16x32_bf16 v[12:15], v[156:159], v[242:245], 0
	v_mfma_f32_16x16x32_bf16 v[12:15], v[152:155], v[246:249], v[12:15]
	v_mfma_f32_16x16x32_bf16 v[8:11], v[174:177], v[242:245], 0
	v_mfma_f32_16x16x32_bf16 v[8:11], v[170:173], v[246:249], v[8:11]
	v_cndmask_b32_e64 v132, 0, 1, s[8:9]
	v_cmp_ne_u32_e64 s[38:39], 1, v132
	s_andn2_b64 vcc, exec, s[8:9]
	s_mov_b64 s[60:61], -1
	s_cbranch_vccnz .Lpk_s1108_1111
	v_mfma_f32_16x16x32_bf16 v[132:135], v[166:169], v[182:185], v[4:7]
	s_mov_b64 s[60:61], 0
	v_mfma_f32_16x16x32_bf16 v[140:143], v[174:177], v[182:185], v[0:3]
	v_mfma_f32_16x16x32_bf16 v[132:135], v[162:165], v[178:181], v[132:135]
	v_mfma_f32_16x16x32_bf16 v[140:143], v[170:173], v[178:181], v[140:143]

; #define GAS __attribute__((address_space(1)))
; #define PG8_ABASE(u) ((const GAS char*)g.A + (size_t)(u).pm * tstepA + (size_t)((u).pn / g.a_tpg) * (size_t)K * 2 + PG8_KOFF(u))
; #define PG8_BBASE(u) ((const GAS char*)g.Bt + (size_t)(u).pn * tstepB + PG8_KOFF(u))
; #define PG8_ABASE(u) ((const GAS char*)g.A + (size_t)(u).pm * tstepA + (size_t)((u).pn / g.a_tpg) * (size_t)K * 2 + PG8_KOFF(u))
; #define PG8_BBASE(u) ((const GAS char*)g.Bt + (size_t)(u).pn * tstepB + PG8_KOFF(u))
; #define PG8_SBASE(u) ((const GAS char*)g.A + (size_t)(u).srow * (size_t)lda * 2 + (size_t)((u).pn / g.a_tpg) * (size_t)K * 2 + PG8_KOFF(u))
; template <class Epi, class Sched>
; __device__ __forceinline__ void gemm_phase_strip(PG8_LAS unsigned char* lds, PG8_LAS unsigned char* slds, PG8_LAS unsigned char* pf, const Gemm g, const Sched& S, const Epi& E, int wv) {
;     ...
;         const bool has_next = S.next(ui + 1, nxt);
;         const GAS char* nA = has_next ? PG8_ABASE(nxt) : cA; const GAS char* nB = has_next ? PG8_BBASE(nxt) : cB; const GAS char* nS = has_next ? PG8_SBASE(nxt) : cS;
;         if constexpr (Sched::SPLIT) { if (has_next && nxt.kh > 0) nA += hstepA; }
;         int ntu = nt; if constexpr (Sched::SPLIT) { if (cur.kh >= 0) ntu = nt >> 1; }
;     ...
; #pragma unroll
;         for (int a = 0; a < 2; ++a)
; #pragma unroll
;             for (int b = 0; b < 2; ++b)
; #pragma unroll
;                 for (int m = 0; m < 4; ++m)
; #pragma unroll
;                     for (int n = 0; n < 2; ++n) acc[a][b][m][n] = (f32x4){0.f, 0.f, 0.f, 0.f};
;         accS[0] = (f32x4){0.f, 0.f, 0.f, 0.f}; accS[1] = (f32x4){0.f, 0.f, 0.f, 0.f};
;         cur = nxt; cA = nA; cB = nB; cS = nS; if constexpr (Sched::SPLIT) hsA = cur.kh > 0 ? -(long)hstepA : (long)hstepA; ++ui; par ^= 1;
.LBB0_1303:
	s_ashr_i32 s11, s10, 31
	s_lshl_b64 s[20:21], s[10:11], 20
	s_add_u32 s50, s60, s20
	s_addc_u32 s51, s61, s21
	s_and_b64 s[20:21], s[38:39], exec
	s_cselect_b32 s1, s51, s53
	s_cselect_b32 s5, s50, s52
	s_add_u32 s11, s54, 0x100
	s_addc_u32 s13, s55, 0
	s_add_u32 s20, s52, 0x100
	s_addc_u32 s21, s53, 0
	s_add_u32 s22, s14, 0x80080
	v_mov_b32_e32 v160, v161
	s_addc_u32 s23, s15, 0
	v_mov_b32_e32 v162, v161
	v_mov_b32_e32 v163, v161
	v_mov_b64_e32 v[4:5], v[160:161]
	s_waitcnt lgkmcnt(0)
	v_mov_b64_e32 v[0:1], v[160:161]
	v_lshl_add_u64 v[218:219], s[22:23], 0, v[214:215]
	v_lshl_add_u64 v[220:221], s[22:23], 0, v[216:217]
	s_mov_b32 s22, -2
	s_mov_b64 s[52:53], 0
	v_mov_b64_e32 v[6:7], v[162:163]
	v_mov_b64_e32 v[2:3], v[162:163]
	s_branch .Lpeel_s1304

; #define GAS __attribute__((address_space(1)))
; #define PG8_STAGE(bufoff, gbase, voff) do { _Pragma("unroll") for (int _i = 0; _i < 2; ++_i) \
;         __builtin_amdgcn_global_load_lds((const GAS unsigned*)((const GAS char*)(gbase) + (voff)[_i]), (PG8_LAS unsigned*)(lds + (bufoff) + ldsw + _i * 8192), 16, 0, 0); } while (0)
; #define PG8_LDA(dst, b, h) do { _Pragma("unroll") for (int m = 0; m < 4; ++m) _Pragma("unroll") for (int k = 0; k < 2; ++k) dst[m][k] = *(const PG8_LAS bf16x8*)(lds + PG8_SA(b, h) + aoff + m * 2048 + k * 1024); } while (0)
; #define PG8_LDB(dst, b, h) do { _Pragma("unroll") for (int n = 0; n < 2; ++n) _Pragma("unroll") for (int k = 0; k < 2; ++k) dst[n][k] = *(const PG8_LAS bf16x8*)(lds + PG8_SB(b, h) + boff + n * 2048 + k * 1024); } while (0)
; #define PG8_MMA(ai, bj, At, Bt) do { __builtin_amdgcn_s_setprio(1); _Pragma("unroll") for (int m = 0; m < 4; ++m) _Pragma("unroll") for (int n = 0; n < 2; ++n) _Pragma("unroll") for (int k = 0; k < 2; ++k) \
;         acc[ai][bj][m][n] = __builtin_amdgcn_mfma_f32_16x16x32_bf16(Bt[n][k], At[m][k], acc[ai][bj][m][n], 0, 0, 0); __builtin_amdgcn_s_setprio(0); } while (0)
; #define PG8_WAIT_V(n) asm volatile("s_waitcnt vmcnt(" #n ")" ::: "memory")
; #define PG8_WAIT_L(n) asm volatile("s_waitcnt lgkmcnt(" #n ")" ::: "memory")
; #define PG8_BAR __builtin_amdgcn_s_barrier()
; #define PG8_SCHED __builtin_amdgcn_sched_barrier(0)
; #define PG8_WAIT_V(n) asm volatile("s_waitcnt vmcnt(" #n ")" ::: "memory")
; template <class Epi, class Sched>
; __device__ __forceinline__ void gemm_phase_strip(PG8_LAS unsigned char* lds, PG8_LAS unsigned char* slds, PG8_LAS unsigned char* pf, const Gemm g, const Sched& S, const Epi& E, int wv) {
;     ...
;         for (int t = 0; t < ntu; t += 2) {
;             const bool last = (t == ntu - 2);
;             const GAS char* a1 = cA + (size_t)(t + 1) * kstep;
;             const GAS char* a2 = last ? nA : cA + (size_t)(t + 2) * kstep; const GAS char* b2 = last ? nB : cB + (size_t)(t + 2) * kstep; const GAS char* s2 = last ? nS : cS + (size_t)(t + 2) * kstep;
;             const GAS char* a3 = a2 + kstep; const GAS char* b3 = b2 + kstep;
;             PG8_LDB(B0, 0, 0); PG8_LDB(B1, 0, 1); PG8_SCHED; PG8_LDA(At, 0, 0); PG8_STAGE(PG8_SA(1, 1), a1 + PG8_HS, voffA);
;             PG8_WAIT_V(8); PG8_WAIT_L(0); PG8_BAR; PG8_MMA(0, 0, At, B0); PG8_MMA(0, 1, At, B1); PG8_BAR; PG8_SCHED;
.Lpeel_s1304:
	s_add_u32 s23, s14, s52
	s_addc_u32 s24, s15, s53
	s_add_u32 s23, s23, 0x100
	s_addc_u32 s28, s24, 0
	s_add_u32 s31, s20, s52
	s_addc_u32 s38, s21, s53
	s_add_i32 s39, 0, 0x10000
	s_add_i32 s41, 0, 0x14000
	v_add_u32_e32 v128, s39, v233
	ds_read_b128 v[148:151], v128
	ds_read_b128 v[144:147], v128 offset:1024
	ds_read_b128 v[166:169], v128 offset:2048
	ds_read_b128 v[162:165], v128 offset:3072
	v_add_u32_e32 v128, s41, v233
	ds_read_b128 v[156:159], v128
	ds_read_b128 v[152:155], v128 offset:1024
	ds_read_b128 v[174:177], v128 offset:2048
	ds_read_b128 v[170:173], v128 offset:3072
	s_cmpk_eq_i32 s52, 0xf00
	s_cselect_b64 s[56:57], -1, 0
	s_and_b64 s[24:25], s[56:57], exec
	s_cselect_b32 s29, s43, s28
	s_cselect_b32 s28, s42, s23
	s_cselect_b32 s55, s1, s38
	s_cselect_b32 s54, s5, s31
	v_lshl_add_u64 v[222:223], v[220:221], 0, s[52:53]
	s_add_i32 m0, s64, 0xc000
	ds_read_b128 v[128:131], v236
	ds_read_b128 v[136:139], v236 offset:1024
	ds_read_b128 v[178:181], v236 offset:2048
	ds_read_b128 v[182:185], v236 offset:3072
	ds_read_b128 v[186:189], v236 offset:4096
	ds_read_b128 v[190:193], v236 offset:5120
	ds_read_b128 v[194:197], v236 offset:6144
	ds_read_b128 v[198:201], v236 offset:7168
	global_load_lds_dwordx4 v[222:223], off
	v_lshl_add_u64 v[222:223], v[218:219], 0, s[52:53]
	s_add_i32 m0, s64, 0xe000
	s_nop 0
	global_load_lds_dwordx4 v[222:223], off
	s_waitcnt vmcnt(8)
	s_waitcnt lgkmcnt(0)
	s_barrier
	s_waitcnt lgkmcnt(0)
	v_mfma_f32_16x16x32_bf16 v[140:143], v[148:151], v[128:131], 0
	v_mfma_f32_16x16x32_bf16 v[140:143], v[144:147], v[136:139], v[140:143]
	v_mfma_f32_16x16x32_bf16 v[132:135], v[166:169], v[128:131], 0
	v_mfma_f32_16x16x32_bf16 v[132:135], v[162:165], v[136:139], v[132:135]
	v_mfma_f32_16x16x32_bf16 v[124:127], v[148:151], v[178:181], 0
	v_mfma_f32_16x16x32_bf16 v[124:127], v[144:147], v[182:185], v[124:127]
	v_mfma_f32_16x16x32_bf16 v[120:123], v[166:169], v[178:181], 0
	v_mfma_f32_16x16x32_bf16 v[120:123], v[162:165], v[182:185], v[120:123]
	v_mfma_f32_16x16x32_bf16 v[116:119], v[148:151], v[186:189], 0
	v_mfma_f32_16x16x32_bf16 v[116:119], v[144:147], v[190:193], v[116:119]
	v_mfma_f32_16x16x32_bf16 v[112:115], v[166:169], v[186:189], 0
	v_mfma_f32_16x16x32_bf16 v[112:115], v[162:165], v[190:193], v[112:115]
	v_mfma_f32_16x16x32_bf16 v[108:111], v[148:151], v[194:197], 0
	v_mfma_f32_16x16x32_bf16 v[108:111], v[144:147], v[198:201], v[108:111]
	v_mfma_f32_16x16x32_bf16 v[104:107], v[166:169], v[194:197], 0
	v_mfma_f32_16x16x32_bf16 v[104:107], v[162:165], v[198:201], v[104:107]
	v_mfma_f32_16x16x32_bf16 v[68:71], v[156:159], v[128:131], 0
	v_mfma_f32_16x16x32_bf16 v[68:71], v[152:155], v[136:139], v[68:71]
	v_mfma_f32_16x16x32_bf16 v[64:67], v[174:177], v[128:131], 0
	v_mfma_f32_16x16x32_bf16 v[64:67], v[170:173], v[136:139], v[64:67]
	v_mfma_f32_16x16x32_bf16 v[60:63], v[156:159], v[178:181], 0
	v_mfma_f32_16x16x32_bf16 v[60:63], v[152:155], v[182:185], v[60:63]
	v_mfma_f32_16x16x32_bf16 v[56:59], v[174:177], v[178:181], 0
	v_mfma_f32_16x16x32_bf16 v[56:59], v[170:173], v[182:185], v[56:59]
	v_mfma_f32_16x16x32_bf16 v[52:55], v[156:159], v[186:189], 0
	v_mfma_f32_16x16x32_bf16 v[52:55], v[152:155], v[190:193], v[52:55]
	v_mfma_f32_16x16x32_bf16 v[48:51], v[174:177], v[186:189], 0
	v_mfma_f32_16x16x32_bf16 v[48:51], v[170:173], v[190:193], v[48:51]
	v_mfma_f32_16x16x32_bf16 v[44:47], v[156:159], v[194:197], 0
	v_mfma_f32_16x16x32_bf16 v[44:47], v[152:155], v[198:201], v[44:47]
	v_mfma_f32_16x16x32_bf16 v[40:43], v[174:177], v[194:197], 0
	v_mfma_f32_16x16x32_bf16 v[40:43], v[170:173], v[198:201], v[40:43]
	s_barrier
; #define PG8_STAGE(bufoff, gbase, voff) do { _Pragma("unroll") for (int _i = 0; _i < 2; ++_i) \
;         __builtin_amdgcn_global_load_lds((const GAS unsigned*)((const GAS char*)(gbase) + (voff)[_i]), (PG8_LAS unsigned*)(lds + (bufoff) + ldsw + _i * 8192), 16, 0, 0); } while (0)
; #define PG8_LDA(dst, b, h) do { _Pragma("unroll") for (int m = 0; m < 4; ++m) _Pragma("unroll") for (int k = 0; k < 2; ++k) dst[m][k] = *(const PG8_LAS bf16x8*)(lds + PG8_SA(b, h) + aoff + m * 2048 + k * 1024); } while (0)
; #define PG8_MMA(ai, bj, At, Bt) do { __builtin_amdgcn_s_setprio(1); _Pragma("unroll") for (int m = 0; m < 4; ++m) _Pragma("unroll") for (int n = 0; n < 2; ++n) _Pragma("unroll") for (int k = 0; k < 2; ++k) \
;         acc[ai][bj][m][n] = __builtin_amdgcn_mfma_f32_16x16x32_bf16(Bt[n][k], At[m][k], acc[ai][bj][m][n], 0, 0, 0); __builtin_amdgcn_s_setprio(0); } while (0)
; #define PG8_WAIT_V(n) asm volatile("s_waitcnt vmcnt(" #n ")" ::: "memory")
; #define PG8_WAIT_L(n) asm volatile("s_waitcnt lgkmcnt(" #n ")" ::: "memory")
; #define PG8_BAR __builtin_amdgcn_s_barrier()
; #define PG8_SCHED __builtin_amdgcn_sched_barrier(0)
; #define PG8_STAGE(bufoff, gbase, voff) do { _Pragma("unroll") for (int _i = 0; _i < 2; ++_i) \
;         __builtin_amdgcn_global_load_lds((const GAS unsigned*)((const GAS char*)(gbase) + (voff)[_i]), (PG8_LAS unsigned*)(lds + (bufoff) + ldsw + _i * 8192), 16, 0, 0); } while (0)
; #define PG8_LDA(dst, b, h) do { _Pragma("unroll") for (int m = 0; m < 4; ++m) _Pragma("unroll") for (int k = 0; k < 2; ++k) dst[m][k] = *(const PG8_LAS bf16x8*)(lds + PG8_SA(b, h) + aoff + m * 2048 + k * 1024); } while (0)
; #define PG8_LDS_S(dst, boffs) do { dst[0] = *(const PG8_LAS bf16x8*)(slds + (boffs) + soff0); dst[1] = *(const PG8_LAS bf16x8*)(slds + (boffs) + (soff0 ^ 64)); } while (0)
; #define PG8_BAR __builtin_amdgcn_s_barrier()
; template <class Epi, class Sched>
; __device__ __forceinline__ void gemm_phase_strip(PG8_LAS unsigned char* lds, PG8_LAS unsigned char* slds, PG8_LAS unsigned char* pf, const Gemm g, const Sched& S, const Epi& E, int wv) {
;     ...
;             PG8_LDA(At, 0, 1); PG8_LDS_S(As, sq); PG8_STAGE(PG8_SB(0, 0), b2, voffB); PG8_STAGE(PG8_SB(0, 1), b2 + hstepB, voffB); PG8_STAGE(PG8_SA(0, 0), a2, voffA);
;             PG8_WAIT_V(8); PG8_WAIT_L(0); PG8_BAR; PG8_MMA(1, 0, At, B0); PG8_MMA(1, 1, At, B1); PG8_MMA_S(); PG8_BAR; PG8_SCHED;
	s_add_i32 s23, s91, 0
	s_add_i32 s23, s23, 0x21000
	v_add_u32_e32 v160, s23, v234
	v_add_u32_e32 v237, s23, v235
	s_add_i32 s23, s39, s62
	v_lshl_add_u64 v[222:223], s[54:55], 0, v[204:205]
	s_mov_b32 m0, s23
	ds_read_b128 v[128:131], v236 offset:16384
	ds_read_b128 v[136:139], v236 offset:17408
	ds_read_b128 v[186:189], v236 offset:18432
	ds_read_b128 v[190:193], v236 offset:19456
	ds_read_b128 v[194:197], v236 offset:20480
	ds_read_b128 v[198:201], v236 offset:21504
	ds_read_b128 v[242:245], v236 offset:22528
	ds_read_b128 v[246:249], v236 offset:23552
	ds_read_b128 v[182:185], v160
	ds_read_b128 v[178:181], v237
	global_load_lds_dwordx4 v[222:223], off
	s_add_i32 m0, s23, 0x2000
	s_add_u32 s24, s54, 0x80000
	v_lshl_add_u64 v[224:225], s[54:55], 0, v[208:209]
	s_addc_u32 s25, s55, 0
	s_add_i32 s23, s41, s62
	global_load_lds_dwordx4 v[224:225], off
	v_lshl_add_u64 v[226:227], s[24:25], 0, v[204:205]
	s_mov_b32 m0, s23
	v_lshl_add_u64 v[228:229], s[28:29], 0, v[206:207]
	global_load_lds_dwordx4 v[226:227], off
	v_lshl_add_u64 v[226:227], s[24:25], 0, v[208:209]
	s_add_i32 m0, s23, 0x2000
	s_nop 0
	global_load_lds_dwordx4 v[226:227], off
	v_lshl_add_u64 v[226:227], s[28:29], 0, v[202:203]
	s_mov_b32 m0, s64
	s_nop 0
	global_load_lds_dwordx4 v[226:227], off
	s_mov_b32 m0, s65
	s_nop 0
	global_load_lds_dwordx4 v[228:229], off
	s_waitcnt vmcnt(8)
	s_waitcnt lgkmcnt(0)
	s_barrier
	s_waitcnt lgkmcnt(0)
	v_mfma_f32_16x16x32_bf16 v[100:103], v[148:151], v[128:131], 0
	v_mfma_f32_16x16x32_bf16 v[100:103], v[144:147], v[136:139], v[100:103]
	v_mfma_f32_16x16x32_bf16 v[96:99], v[166:169], v[128:131], 0
	v_mfma_f32_16x16x32_bf16 v[96:99], v[162:165], v[136:139], v[96:99]
	v_mfma_f32_16x16x32_bf16 v[92:95], v[148:151], v[186:189], 0
	v_mfma_f32_16x16x32_bf16 v[92:95], v[144:147], v[190:193], v[92:95]
	v_mfma_f32_16x16x32_bf16 v[88:91], v[166:169], v[186:189], 0
	v_mfma_f32_16x16x32_bf16 v[88:91], v[162:165], v[190:193], v[88:91]
	v_mfma_f32_16x16x32_bf16 v[84:87], v[148:151], v[194:197], 0
	v_mfma_f32_16x16x32_bf16 v[84:87], v[144:147], v[198:201], v[84:87]
	v_mfma_f32_16x16x32_bf16 v[80:83], v[166:169], v[194:197], 0
	v_mfma_f32_16x16x32_bf16 v[80:83], v[162:165], v[198:201], v[80:83]
	v_mfma_f32_16x16x32_bf16 v[76:79], v[148:151], v[242:245], 0
	v_mfma_f32_16x16x32_bf16 v[76:79], v[144:147], v[246:249], v[76:79]
	v_mfma_f32_16x16x32_bf16 v[72:75], v[166:169], v[242:245], 0
	v_mfma_f32_16x16x32_bf16 v[72:75], v[162:165], v[246:249], v[72:75]
	v_mfma_f32_16x16x32_bf16 v[36:39], v[156:159], v[128:131], 0
	v_mfma_f32_16x16x32_bf16 v[36:39], v[152:155], v[136:139], v[36:39]
	v_mfma_f32_16x16x32_bf16 v[32:35], v[174:177], v[128:131], 0
	v_mfma_f32_16x16x32_bf16 v[32:35], v[170:173], v[136:139], v[32:35]
	v_mfma_f32_16x16x32_bf16 v[28:31], v[156:159], v[186:189], 0
	v_mfma_f32_16x16x32_bf16 v[28:31], v[152:155], v[190:193], v[28:31]
	v_mfma_f32_16x16x32_bf16 v[24:27], v[174:177], v[186:189], 0
	v_mfma_f32_16x16x32_bf16 v[24:27], v[170:173], v[190:193], v[24:27]
	v_mfma_f32_16x16x32_bf16 v[20:23], v[156:159], v[194:197], 0
	v_mfma_f32_16x16x32_bf16 v[20:23], v[152:155], v[198:201], v[20:23]
	v_mfma_f32_16x16x32_bf16 v[16:19], v[174:177], v[194:197], 0
	v_mfma_f32_16x16x32_bf16 v[16:19], v[170:173], v[198:201], v[16:19]
	v_mfma_f32_16x16x32_bf16 v[12:15], v[156:159], v[242:245], 0
	v_mfma_f32_16x16x32_bf16 v[12:15], v[152:155], v[246:249], v[12:15]
	v_mfma_f32_16x16x32_bf16 v[8:11], v[174:177], v[242:245], 0
	v_mfma_f32_16x16x32_bf16 v[8:11], v[170:173], v[246:249], v[8:11]
	v_cndmask_b32_e64 v128, 0, 1, s[8:9]
	v_cmp_ne_u32_e64 s[38:39], 1, v128
	s_andn2_b64 vcc, exec, s[8:9]
	s_mov_b64 s[58:59], -1
	s_cbranch_vccnz .Lpk_s1304_1307
	v_mfma_f32_16x16x32_bf16 v[128:131], v[166:169], v[182:185], v[4:7]
	s_mov_b64 s[58:59], 0
	v_mfma_f32_16x16x32_bf16 v[136:139], v[174:177], v[182:185], v[0:3]
	v_mfma_f32_16x16x32_bf16 v[128:131], v[162:165], v[178:181], v[128:131]
	v_mfma_f32_16x16x32_bf16 v[136:139], v[170:173], v[178:181], v[136:139]

; #define GAS __attribute__((address_space(1)))
; #define PG8_ABASE(u) ((const GAS char*)g.A + (size_t)(u).pm * tstepA + (size_t)((u).pn / g.a_tpg) * (size_t)K * 2 + PG8_KOFF(u))
; #define PG8_BBASE(u) ((const GAS char*)g.Bt + (size_t)(u).pn * tstepB + PG8_KOFF(u))
; #define PG8_ABASE(u) ((const GAS char*)g.A + (size_t)(u).pm * tstepA + (size_t)((u).pn / g.a_tpg) * (size_t)K * 2 + PG8_KOFF(u))
; #define PG8_BBASE(u) ((const GAS char*)g.Bt + (size_t)(u).pn * tstepB + PG8_KOFF(u))
; #define PG8_SBASE(u) ((const GAS char*)g.A + (size_t)(u).srow * (size_t)lda * 2 + (size_t)((u).pn / g.a_tpg) * (size_t)K * 2 + PG8_KOFF(u))
; template <class Epi, class Sched>
; __device__ __forceinline__ void gemm_phase_strip(PG8_LAS unsigned char* lds, PG8_LAS unsigned char* slds, PG8_LAS unsigned char* pf, const Gemm g, const Sched& S, const Epi& E, int wv) {
;     ...
;         const bool has_next = S.next(ui + 1, nxt);
;         const GAS char* nA = has_next ? PG8_ABASE(nxt) : cA; const GAS char* nB = has_next ? PG8_BBASE(nxt) : cB; const GAS char* nS = has_next ? PG8_SBASE(nxt) : cS;
;         if constexpr (Sched::SPLIT) { if (has_next && nxt.kh > 0) nA += hstepA; }
;         int ntu = nt; if constexpr (Sched::SPLIT) { if (cur.kh >= 0) ntu = nt >> 1; }
;     ...
; #pragma unroll
;         for (int a = 0; a < 2; ++a)
; #pragma unroll
;             for (int b = 0; b < 2; ++b)
; #pragma unroll
;                 for (int m = 0; m < 4; ++m)
; #pragma unroll
;                     for (int n = 0; n < 2; ++n) acc[a][b][m][n] = (f32x4){0.f, 0.f, 0.f, 0.f};
;         accS[0] = (f32x4){0.f, 0.f, 0.f, 0.f}; accS[1] = (f32x4){0.f, 0.f, 0.f, 0.f};
;         cur = nxt; cA = nA; cB = nB; cS = nS; if constexpr (Sched::SPLIT) hsA = cur.kh > 0 ? -(long)hstepA : (long)hstepA; ++ui; par ^= 1;
.LBB0_1559:
	s_add_u32 s9, s52, 0x100
	s_addc_u32 s20, s53, 0
	s_add_u32 s21, s14, 0x100
	s_addc_u32 s22, s15, 0
	s_add_u32 s14, s12, 0x160080
	v_mov_b32_e32 v160, v161
	s_addc_u32 s15, s13, 0
	v_mov_b32_e32 v162, v161
	v_mov_b32_e32 v163, v161
	v_mov_b64_e32 v[4:5], v[160:161]
	s_waitcnt lgkmcnt(0)
	v_mov_b64_e32 v[0:1], v[160:161]
	v_lshl_add_u64 v[218:219], s[14:15], 0, v[214:215]
	v_lshl_add_u64 v[220:221], s[14:15], 0, v[216:217]
	s_mov_b32 s23, -2
	s_mov_b64 s[14:15], 0
	v_mov_b64_e32 v[6:7], v[162:163]
	v_mov_b64_e32 v[2:3], v[162:163]
	s_branch .Lpeel_s1560

; #define GAS __attribute__((address_space(1)))
; #define PG8_STAGE(bufoff, gbase, voff) do { _Pragma("unroll") for (int _i = 0; _i < 2; ++_i) \
;         __builtin_amdgcn_global_load_lds((const GAS unsigned*)((const GAS char*)(gbase) + (voff)[_i]), (PG8_LAS unsigned*)(lds + (bufoff) + ldsw + _i * 8192), 16, 0, 0); } while (0)
; #define PG8_LDA(dst, b, h) do { _Pragma("unroll") for (int m = 0; m < 4; ++m) _Pragma("unroll") for (int k = 0; k < 2; ++k) dst[m][k] = *(const PG8_LAS bf16x8*)(lds + PG8_SA(b, h) + aoff + m * 2048 + k * 1024); } while (0)
; #define PG8_LDB(dst, b, h) do { _Pragma("unroll") for (int n = 0; n < 2; ++n) _Pragma("unroll") for (int k = 0; k < 2; ++k) dst[n][k] = *(const PG8_LAS bf16x8*)(lds + PG8_SB(b, h) + boff + n * 2048 + k * 1024); } while (0)
; #define PG8_MMA(ai, bj, At, Bt) do { __builtin_amdgcn_s_setprio(1); _Pragma("unroll") for (int m = 0; m < 4; ++m) _Pragma("unroll") for (int n = 0; n < 2; ++n) _Pragma("unroll") for (int k = 0; k < 2; ++k) \
;         acc[ai][bj][m][n] = __builtin_amdgcn_mfma_f32_16x16x32_bf16(Bt[n][k], At[m][k], acc[ai][bj][m][n], 0, 0, 0); __builtin_amdgcn_s_setprio(0); } while (0)
; #define PG8_WAIT_V(n) asm volatile("s_waitcnt vmcnt(" #n ")" ::: "memory")
; #define PG8_WAIT_L(n) asm volatile("s_waitcnt lgkmcnt(" #n ")" ::: "memory")
; #define PG8_BAR __builtin_amdgcn_s_barrier()
; #define PG8_SCHED __builtin_amdgcn_sched_barrier(0)
; #define PG8_WAIT_V(n) asm volatile("s_waitcnt vmcnt(" #n ")" ::: "memory")
; template <class Epi, class Sched>
; __device__ __forceinline__ void gemm_phase_strip(PG8_LAS unsigned char* lds, PG8_LAS unsigned char* slds, PG8_LAS unsigned char* pf, const Gemm g, const Sched& S, const Epi& E, int wv) {
;     ...
;         for (int t = 0; t < ntu; t += 2) {
;             const bool last = (t == ntu - 2);
;             const GAS char* a1 = cA + (size_t)(t + 1) * kstep;
;             const GAS char* a2 = last ? nA : cA + (size_t)(t + 2) * kstep; const GAS char* b2 = last ? nB : cB + (size_t)(t + 2) * kstep; const GAS char* s2 = last ? nS : cS + (size_t)(t + 2) * kstep;
;             const GAS char* a3 = a2 + kstep; const GAS char* b3 = b2 + kstep;
;             PG8_LDB(B0, 0, 0); PG8_LDB(B1, 0, 1); PG8_SCHED; PG8_LDA(At, 0, 0); PG8_STAGE(PG8_SA(1, 1), a1 + PG8_HS, voffA);
;             PG8_WAIT_V(8); PG8_WAIT_L(0); PG8_BAR; PG8_MMA(0, 0, At, B0); PG8_MMA(0, 1, At, B1); PG8_BAR; PG8_SCHED;
.Lpeel_s1560:
	s_add_u32 s24, s12, s14
	s_addc_u32 s25, s13, s15
	s_add_u32 s40, s24, 0x100
	s_addc_u32 s41, s25, 0
	s_add_u32 s52, s21, s14
	s_addc_u32 s53, s22, s15
	s_add_i32 s58, 0, 0x10000
	s_add_i32 s59, 0, 0x14000
	v_add_u32_e32 v136, s58, v233
	ds_read_b128 v[148:151], v136
	ds_read_b128 v[144:147], v136 offset:1024
	ds_read_b128 v[166:169], v136 offset:2048
	ds_read_b128 v[162:165], v136 offset:3072
	v_add_u32_e32 v136, s59, v233
	ds_read_b128 v[156:159], v136
	ds_read_b128 v[152:155], v136 offset:1024
	ds_read_b128 v[174:177], v136 offset:2048
	ds_read_b128 v[170:173], v136 offset:3072
	s_cmpk_eq_i32 s14, 0x2b00
	s_cselect_b64 s[54:55], -1, 0
	s_and_b64 s[24:25], s[54:55], exec
	s_cselect_b32 s57, s11, s41
	s_cselect_b32 s56, s10, s40
	s_cselect_b32 s53, s45, s53
	s_cselect_b32 s52, s44, s52
	v_lshl_add_u64 v[222:223], v[220:221], 0, s[14:15]
	s_add_i32 m0, s66, 0xc000
	ds_read_b128 v[136:139], v236
	ds_read_b128 v[140:143], v236 offset:1024
	ds_read_b128 v[178:181], v236 offset:2048
	ds_read_b128 v[182:185], v236 offset:3072
	ds_read_b128 v[186:189], v236 offset:4096
	ds_read_b128 v[190:193], v236 offset:5120
	ds_read_b128 v[194:197], v236 offset:6144
	ds_read_b128 v[198:201], v236 offset:7168
	global_load_lds_dwordx4 v[222:223], off
	v_lshl_add_u64 v[222:223], v[218:219], 0, s[14:15]
	s_add_i32 m0, s66, 0xe000
	s_nop 0
	global_load_lds_dwordx4 v[222:223], off
	s_waitcnt vmcnt(8)
	s_waitcnt lgkmcnt(0)
	s_barrier
	s_waitcnt lgkmcnt(0)
	v_mfma_f32_16x16x32_bf16 v[132:135], v[148:151], v[136:139], 0
	v_mfma_f32_16x16x32_bf16 v[132:135], v[144:147], v[140:143], v[132:135]
	v_mfma_f32_16x16x32_bf16 v[128:131], v[166:169], v[136:139], 0
	v_mfma_f32_16x16x32_bf16 v[128:131], v[162:165], v[140:143], v[128:131]
	v_mfma_f32_16x16x32_bf16 v[124:127], v[148:151], v[178:181], 0
	v_mfma_f32_16x16x32_bf16 v[124:127], v[144:147], v[182:185], v[124:127]
	v_mfma_f32_16x16x32_bf16 v[120:123], v[166:169], v[178:181], 0
	v_mfma_f32_16x16x32_bf16 v[120:123], v[162:165], v[182:185], v[120:123]
	v_mfma_f32_16x16x32_bf16 v[116:119], v[148:151], v[186:189], 0
	v_mfma_f32_16x16x32_bf16 v[116:119], v[144:147], v[190:193], v[116:119]
	v_mfma_f32_16x16x32_bf16 v[112:115], v[166:169], v[186:189], 0
	v_mfma_f32_16x16x32_bf16 v[112:115], v[162:165], v[190:193], v[112:115]
	v_mfma_f32_16x16x32_bf16 v[108:111], v[148:151], v[194:197], 0
	v_mfma_f32_16x16x32_bf16 v[108:111], v[144:147], v[198:201], v[108:111]
	v_mfma_f32_16x16x32_bf16 v[104:107], v[166:169], v[194:197], 0
	v_mfma_f32_16x16x32_bf16 v[104:107], v[162:165], v[198:201], v[104:107]
	v_mfma_f32_16x16x32_bf16 v[68:71], v[156:159], v[136:139], 0
	v_mfma_f32_16x16x32_bf16 v[68:71], v[152:155], v[140:143], v[68:71]
	v_mfma_f32_16x16x32_bf16 v[64:67], v[174:177], v[136:139], 0
	v_mfma_f32_16x16x32_bf16 v[64:67], v[170:173], v[140:143], v[64:67]
	v_mfma_f32_16x16x32_bf16 v[60:63], v[156:159], v[178:181], 0
	v_mfma_f32_16x16x32_bf16 v[60:63], v[152:155], v[182:185], v[60:63]
	v_mfma_f32_16x16x32_bf16 v[56:59], v[174:177], v[178:181], 0
	v_mfma_f32_16x16x32_bf16 v[56:59], v[170:173], v[182:185], v[56:59]
	v_mfma_f32_16x16x32_bf16 v[52:55], v[156:159], v[186:189], 0
	v_mfma_f32_16x16x32_bf16 v[52:55], v[152:155], v[190:193], v[52:55]
	v_mfma_f32_16x16x32_bf16 v[48:51], v[174:177], v[186:189], 0
	v_mfma_f32_16x16x32_bf16 v[48:51], v[170:173], v[190:193], v[48:51]
	v_mfma_f32_16x16x32_bf16 v[44:47], v[156:159], v[194:197], 0
	v_mfma_f32_16x16x32_bf16 v[44:47], v[152:155], v[198:201], v[44:47]
	v_mfma_f32_16x16x32_bf16 v[40:43], v[174:177], v[194:197], 0
	v_mfma_f32_16x16x32_bf16 v[40:43], v[170:173], v[198:201], v[40:43]
	s_barrier
; #define PG8_STAGE(bufoff, gbase, voff) do { _Pragma("unroll") for (int _i = 0; _i < 2; ++_i) \
;         __builtin_amdgcn_global_load_lds((const GAS unsigned*)((const GAS char*)(gbase) + (voff)[_i]), (PG8_LAS unsigned*)(lds + (bufoff) + ldsw + _i * 8192), 16, 0, 0); } while (0)
; #define PG8_LDA(dst, b, h) do { _Pragma("unroll") for (int m = 0; m < 4; ++m) _Pragma("unroll") for (int k = 0; k < 2; ++k) dst[m][k] = *(const PG8_LAS bf16x8*)(lds + PG8_SA(b, h) + aoff + m * 2048 + k * 1024); } while (0)
; #define PG8_MMA(ai, bj, At, Bt) do { __builtin_amdgcn_s_setprio(1); _Pragma("unroll") for (int m = 0; m < 4; ++m) _Pragma("unroll") for (int n = 0; n < 2; ++n) _Pragma("unroll") for (int k = 0; k < 2; ++k) \
;         acc[ai][bj][m][n] = __builtin_amdgcn_mfma_f32_16x16x32_bf16(Bt[n][k], At[m][k], acc[ai][bj][m][n], 0, 0, 0); __builtin_amdgcn_s_setprio(0); } while (0)
; #define PG8_WAIT_V(n) asm volatile("s_waitcnt vmcnt(" #n ")" ::: "memory")
; #define PG8_WAIT_L(n) asm volatile("s_waitcnt lgkmcnt(" #n ")" ::: "memory")
; #define PG8_BAR __builtin_amdgcn_s_barrier()
; #define PG8_SCHED __builtin_amdgcn_sched_barrier(0)
; #define PG8_STAGE(bufoff, gbase, voff) do { _Pragma("unroll") for (int _i = 0; _i < 2; ++_i) \
;         __builtin_amdgcn_global_load_lds((const GAS unsigned*)((const GAS char*)(gbase) + (voff)[_i]), (PG8_LAS unsigned*)(lds + (bufoff) + ldsw + _i * 8192), 16, 0, 0); } while (0)
; #define PG8_LDA(dst, b, h) do { _Pragma("unroll") for (int m = 0; m < 4; ++m) _Pragma("unroll") for (int k = 0; k < 2; ++k) dst[m][k] = *(const PG8_LAS bf16x8*)(lds + PG8_SA(b, h) + aoff + m * 2048 + k * 1024); } while (0)
; #define PG8_LDS_S(dst, boffs) do { dst[0] = *(const PG8_LAS bf16x8*)(slds + (boffs) + soff0); dst[1] = *(const PG8_LAS bf16x8*)(slds + (boffs) + (soff0 ^ 64)); } while (0)
; #define PG8_BAR __builtin_amdgcn_s_barrier()
; template <class Epi, class Sched>
; __device__ __forceinline__ void gemm_phase_strip(PG8_LAS unsigned char* lds, PG8_LAS unsigned char* slds, PG8_LAS unsigned char* pf, const Gemm g, const Sched& S, const Epi& E, int wv) {
;     ...
;             PG8_LDA(At, 0, 1); PG8_LDS_S(As, sq); PG8_STAGE(PG8_SB(0, 0), b2, voffB); PG8_STAGE(PG8_SB(0, 1), b2 + hstepB, voffB); PG8_STAGE(PG8_SA(0, 0), a2, voffA);
;             PG8_WAIT_V(8); PG8_WAIT_L(0); PG8_BAR; PG8_MMA(1, 0, At, B0); PG8_MMA(1, 1, At, B1); PG8_MMA_S(); PG8_BAR; PG8_SCHED;
	s_add_i32 s24, s74, 0
	s_add_i32 s24, s24, 0x21000
	v_add_u32_e32 v160, s24, v234
	v_add_u32_e32 v237, s24, v235
	s_add_i32 s24, s58, s64
	v_lshl_add_u64 v[222:223], s[52:53], 0, v[204:205]
	s_mov_b32 m0, s24
	ds_read_b128 v[136:139], v236 offset:16384
	ds_read_b128 v[140:143], v236 offset:17408
	ds_read_b128 v[186:189], v236 offset:18432
	ds_read_b128 v[190:193], v236 offset:19456
	ds_read_b128 v[194:197], v236 offset:20480
	ds_read_b128 v[198:201], v236 offset:21504
	ds_read_b128 v[242:245], v236 offset:22528
	ds_read_b128 v[246:249], v236 offset:23552
	ds_read_b128 v[182:185], v160
	ds_read_b128 v[178:181], v237
	global_load_lds_dwordx4 v[222:223], off
	s_add_i32 m0, s24, 0x2000
	s_add_u32 s24, s52, 0x160000
	v_lshl_add_u64 v[224:225], s[52:53], 0, v[208:209]
	s_addc_u32 s25, s53, 0
	s_add_i32 s40, s59, s64
	global_load_lds_dwordx4 v[224:225], off
	v_lshl_add_u64 v[226:227], s[24:25], 0, v[204:205]
	s_mov_b32 m0, s40
	v_lshl_add_u64 v[228:229], s[56:57], 0, v[206:207]
	global_load_lds_dwordx4 v[226:227], off
	v_lshl_add_u64 v[226:227], s[24:25], 0, v[208:209]
	s_add_i32 m0, s40, 0x2000
	s_nop 0
	global_load_lds_dwordx4 v[226:227], off
	v_lshl_add_u64 v[226:227], s[56:57], 0, v[202:203]
	s_mov_b32 m0, s66
	s_nop 0
	global_load_lds_dwordx4 v[226:227], off
	s_mov_b32 m0, s67
	s_nop 0
	global_load_lds_dwordx4 v[228:229], off
	s_waitcnt vmcnt(8)
	s_waitcnt lgkmcnt(0)
	s_barrier
	s_waitcnt lgkmcnt(0)
	v_mfma_f32_16x16x32_bf16 v[100:103], v[148:151], v[136:139], 0
	v_mfma_f32_16x16x32_bf16 v[100:103], v[144:147], v[140:143], v[100:103]
	v_mfma_f32_16x16x32_bf16 v[96:99], v[166:169], v[136:139], 0
	v_mfma_f32_16x16x32_bf16 v[96:99], v[162:165], v[140:143], v[96:99]
	v_mfma_f32_16x16x32_bf16 v[92:95], v[148:151], v[186:189], 0
	v_mfma_f32_16x16x32_bf16 v[92:95], v[144:147], v[190:193], v[92:95]
	v_mfma_f32_16x16x32_bf16 v[88:91], v[166:169], v[186:189], 0
	v_mfma_f32_16x16x32_bf16 v[88:91], v[162:165], v[190:193], v[88:91]
	v_mfma_f32_16x16x32_bf16 v[84:87], v[148:151], v[194:197], 0
	v_mfma_f32_16x16x32_bf16 v[84:87], v[144:147], v[198:201], v[84:87]
	v_mfma_f32_16x16x32_bf16 v[80:83], v[166:169], v[194:197], 0
	v_mfma_f32_16x16x32_bf16 v[80:83], v[162:165], v[198:201], v[80:83]
	v_mfma_f32_16x16x32_bf16 v[76:79], v[148:151], v[242:245], 0
	v_mfma_f32_16x16x32_bf16 v[76:79], v[144:147], v[246:249], v[76:79]
	v_mfma_f32_16x16x32_bf16 v[72:75], v[166:169], v[242:245], 0
	v_mfma_f32_16x16x32_bf16 v[72:75], v[162:165], v[246:249], v[72:75]
	v_mfma_f32_16x16x32_bf16 v[36:39], v[156:159], v[136:139], 0
	v_mfma_f32_16x16x32_bf16 v[36:39], v[152:155], v[140:143], v[36:39]
	v_mfma_f32_16x16x32_bf16 v[32:35], v[174:177], v[136:139], 0
	v_mfma_f32_16x16x32_bf16 v[32:35], v[170:173], v[140:143], v[32:35]
	v_mfma_f32_16x16x32_bf16 v[28:31], v[156:159], v[186:189], 0
	v_mfma_f32_16x16x32_bf16 v[28:31], v[152:155], v[190:193], v[28:31]
	v_mfma_f32_16x16x32_bf16 v[24:27], v[174:177], v[186:189], 0
	v_mfma_f32_16x16x32_bf16 v[24:27], v[170:173], v[190:193], v[24:27]
	v_mfma_f32_16x16x32_bf16 v[20:23], v[156:159], v[194:197], 0
	v_mfma_f32_16x16x32_bf16 v[20:23], v[152:155], v[198:201], v[20:23]
	v_mfma_f32_16x16x32_bf16 v[16:19], v[174:177], v[194:197], 0
	v_mfma_f32_16x16x32_bf16 v[16:19], v[170:173], v[198:201], v[16:19]
	v_mfma_f32_16x16x32_bf16 v[12:15], v[156:159], v[242:245], 0
	v_mfma_f32_16x16x32_bf16 v[12:15], v[152:155], v[246:249], v[12:15]
	v_mfma_f32_16x16x32_bf16 v[8:11], v[174:177], v[242:245], 0
	v_mfma_f32_16x16x32_bf16 v[8:11], v[170:173], v[246:249], v[8:11]
	v_cndmask_b32_e64 v136, 0, 1, s[30:31]
	v_cmp_ne_u32_e64 s[40:41], 1, v136
	s_andn2_b64 vcc, exec, s[30:31]
	s_mov_b64 s[58:59], -1
	s_cbranch_vccnz .Lpk_s1560_1563
	v_mfma_f32_16x16x32_bf16 v[136:139], v[166:169], v[182:185], v[4:7]
	s_mov_b64 s[58:59], 0
	v_mfma_f32_16x16x32_bf16 v[140:143], v[174:177], v[182:185], v[0:3]
	v_mfma_f32_16x16x32_bf16 v[136:139], v[162:165], v[178:181], v[136:139]
	v_mfma_f32_16x16x32_bf16 v[140:143], v[170:173], v[178:181], v[140:143]
